# down and out_proj GEMM epilogues: 16-byte merged stores (and 16-byte residual loads in down) via v_permlane16_swap
# speedup vs baseline: 1.0086x; 1.0086x over previous
.LBB0_1924:
	s_or_b64 exec, exec, s[24:25]
	v_lshl_add_u64 v[68:69], v[204:205], 2, v[68:69]
	global_load_dwordx4 v[80:83], v[68:69], off nt
	global_load_dwordx4 v[76:79], v[68:69], off offset:64 nt
	global_load_dwordx4 v[72:75], v[68:69], off offset:512 nt
	s_nop 0
	global_load_dwordx4 v[68:71], v[68:69], off offset:576 nt
	v_lshlrev_b64 v[134:135], 11, v[134:135]
	s_waitcnt vmcnt(0)
	v_lshl_add_u64 v[134:135], s[44:45], 0, v[134:135]
	v_pk_fma_f32 v[50:51], v[114:115], s[14:15], v[50:51] op_sel_hi:[1,0,1]
	v_pk_fma_f32 v[48:49], v[112:113], s[14:15], v[48:49] op_sel_hi:[1,0,1]
	v_lshl_add_u64 v[134:135], v[134:135], 0, v[202:203]
	v_cvt_pk_bf16_f32 v48, v48, v49
	v_cvt_pk_bf16_f32 v49, v50, v51
	v_pk_fma_f32 v[62:63], v[126:127], s[14:15], v[62:63] op_sel_hi:[1,0,1]
	v_pk_fma_f32 v[34:35], v[98:99], s[14:15], v[34:35] op_sel_hi:[1,0,1]
	v_pk_fma_f32 v[32:33], v[96:97], s[14:15], v[32:33] op_sel_hi:[1,0,1]
	v_pk_fma_f32 v[14:15], v[66:67], s[14:15], v[14:15] op_sel_hi:[1,0,1]
	v_cvt_pk_bf16_f32 v32, v32, v33
	v_cvt_pk_bf16_f32 v33, v34, v35
	v_pk_fma_f32 v[12:13], v[64:65], s[14:15], v[12:13] op_sel_hi:[1,0,1]
	v_pk_fma_f32 v[60:61], v[124:125], s[14:15], v[60:61] op_sel_hi:[1,0,1]
	v_cvt_pk_bf16_f32 v12, v12, v13
	v_cvt_pk_bf16_f32 v13, v14, v15
	v_pk_fma_f32 v[58:59], v[122:123], s[14:15], v[58:59] op_sel_hi:[1,0,1]
	v_pk_fma_f32 v[56:57], v[120:121], s[14:15], v[56:57] op_sel_hi:[1,0,1]
	v_pk_fma_f32 v[54:55], v[118:119], s[14:15], v[54:55] op_sel_hi:[1,0,1]
	v_pk_fma_f32 v[52:53], v[116:117], s[14:15], v[52:53] op_sel_hi:[1,0,1]
	v_pk_fma_f32 v[46:47], v[110:111], s[14:15], v[46:47] op_sel_hi:[1,0,1]
	v_pk_fma_f32 v[44:45], v[108:109], s[14:15], v[44:45] op_sel_hi:[1,0,1]
	v_pk_fma_f32 v[42:43], v[106:107], s[14:15], v[42:43] op_sel_hi:[1,0,1]
	v_pk_fma_f32 v[40:41], v[104:105], s[14:15], v[40:41] op_sel_hi:[1,0,1]
	v_pk_fma_f32 v[38:39], v[102:103], s[14:15], v[38:39] op_sel_hi:[1,0,1]
	v_pk_fma_f32 v[36:37], v[100:101], s[14:15], v[36:37] op_sel_hi:[1,0,1]
	v_pk_fma_f32 v[30:31], v[94:95], s[14:15], v[30:31] op_sel_hi:[1,0,1]
	v_pk_fma_f32 v[28:29], v[92:93], s[14:15], v[28:29] op_sel_hi:[1,0,1]
	v_pk_fma_f32 v[26:27], v[90:91], s[14:15], v[26:27] op_sel_hi:[1,0,1]
	v_pk_fma_f32 v[24:25], v[88:89], s[14:15], v[24:25] op_sel_hi:[1,0,1]
	v_pk_fma_f32 v[22:23], v[86:87], s[14:15], v[22:23] op_sel_hi:[1,0,1]
	v_pk_fma_f32 v[20:21], v[84:85], s[14:15], v[20:21] op_sel_hi:[1,0,1]
	v_cvt_pk_bf16_f32 v60, v60, v61
	v_cvt_pk_bf16_f32 v61, v62, v63
	v_cvt_pk_bf16_f32 v56, v56, v57
	v_cvt_pk_bf16_f32 v57, v58, v59
	v_cvt_pk_bf16_f32 v52, v52, v53
	v_cvt_pk_bf16_f32 v53, v54, v55
	v_cvt_pk_bf16_f32 v44, v44, v45
	v_cvt_pk_bf16_f32 v45, v46, v47
	v_cvt_pk_bf16_f32 v40, v40, v41
	v_cvt_pk_bf16_f32 v41, v42, v43
	v_cvt_pk_bf16_f32 v36, v36, v37
	v_cvt_pk_bf16_f32 v37, v38, v39
	v_cvt_pk_bf16_f32 v28, v28, v29
	v_cvt_pk_bf16_f32 v29, v30, v31
	v_cvt_pk_bf16_f32 v24, v24, v25
	v_cvt_pk_bf16_f32 v25, v26, v27
	v_cvt_pk_bf16_f32 v20, v20, v21
	v_cvt_pk_bf16_f32 v21, v22, v23
	s_and_b64 vcc, exec, s[42:43]
	s_mov_b32 s25, s16
	s_mov_b32 s24, s18
	s_mov_b64 s[28:29], s[22:23]
	s_mov_b64 s[26:27], s[20:21]
	v_mov_b32_e32 v224, v48
	v_mov_b32_e32 v225, v49
	v_lshlrev_b64 v[48:49], 11, v[132:133]
	v_lshl_add_u64 v[48:49], s[44:45], 0, v[48:49]
	v_lshl_add_u64 v[48:49], v[48:49], 0, v[202:203]
	v_mov_b32_e32 v228, v32
	v_mov_b32_e32 v229, v33
	v_lshlrev_b64 v[32:33], 11, v[130:131]
	v_lshl_add_u64 v[32:33], s[44:45], 0, v[32:33]
	v_lshl_add_u64 v[32:33], v[32:33], 0, v[202:203]
	v_mov_b32_e32 v232, v12
	v_mov_b32_e32 v233, v13
	v_lshlrev_b64 v[12:13], 11, v[128:129]
	v_lshl_add_u64 v[12:13], s[44:45], 0, v[12:13]
	v_pk_fma_f32 v[14:15], v[82:83], s[14:15], v[18:19] op_sel_hi:[1,0,1]
	v_pk_fma_f32 v[16:17], v[80:81], s[14:15], v[16:17] op_sel_hi:[1,0,1]
	v_pk_fma_f32 v[10:11], v[78:79], s[14:15], v[10:11] op_sel_hi:[1,0,1]
	v_pk_fma_f32 v[8:9], v[76:77], s[14:15], v[8:9] op_sel_hi:[1,0,1]
	v_pk_fma_f32 v[6:7], v[74:75], s[14:15], v[6:7] op_sel_hi:[1,0,1]
	v_pk_fma_f32 v[4:5], v[72:73], s[14:15], v[4:5] op_sel_hi:[1,0,1]
	v_pk_fma_f32 v[2:3], v[70:71], s[14:15], v[2:3] op_sel_hi:[1,0,1]
	v_pk_fma_f32 v[0:1], v[68:69], s[14:15], v[0:1] op_sel_hi:[1,0,1]
	v_lshl_add_u64 v[12:13], v[12:13], 0, v[202:203]
	v_cvt_pk_bf16_f32 v16, v16, v17
	v_cvt_pk_bf16_f32 v17, v14, v15
	v_cvt_pk_bf16_f32 v8, v8, v9
	v_cvt_pk_bf16_f32 v9, v10, v11
	v_cvt_pk_bf16_f32 v4, v4, v5
	v_cvt_pk_bf16_f32 v5, v6, v7
	v_cvt_pk_bf16_f32 v0, v0, v1
	v_cvt_pk_bf16_f32 v1, v2, v3
	v_mov_b32_e32 v238, v60
	v_mov_b32_e32 v239, v61
	v_mov_b32_e32 v236, v56
	v_mov_b32_e32 v237, v57
	s_nop 1
	v_permlane16_swap_b32_e32 v236, v238
	v_permlane16_swap_b32_e32 v237, v239
	global_store_dwordx4 v[134:135], v[236:239], off
	v_mov_b32_e32 v226, v52
	v_mov_b32_e32 v227, v53
	s_nop 1
	v_permlane16_swap_b32_e32 v224, v226
	v_permlane16_swap_b32_e32 v225, v227
	global_store_dwordx4 v[134:135], v[224:227], off offset:256
	v_mov_b32_e32 v242, v44
	v_mov_b32_e32 v243, v45
	v_mov_b32_e32 v240, v40
	v_mov_b32_e32 v241, v41
	s_nop 1
	v_permlane16_swap_b32_e32 v240, v242
	v_permlane16_swap_b32_e32 v241, v243
	global_store_dwordx4 v[48:49], v[240:243], off
	v_mov_b32_e32 v230, v36
	v_mov_b32_e32 v231, v37
	s_nop 1
	v_permlane16_swap_b32_e32 v228, v230
	v_permlane16_swap_b32_e32 v229, v231
	global_store_dwordx4 v[48:49], v[228:231], off offset:256
	v_mov_b32_e32 v226, v28
	v_mov_b32_e32 v227, v29
	v_mov_b32_e32 v224, v24
	v_mov_b32_e32 v225, v25
	s_nop 1
	v_permlane16_swap_b32_e32 v224, v226
	v_permlane16_swap_b32_e32 v225, v227
	global_store_dwordx4 v[32:33], v[224:227], off
	v_mov_b32_e32 v234, v20
	v_mov_b32_e32 v235, v21
	s_nop 1
	v_permlane16_swap_b32_e32 v232, v234
	v_permlane16_swap_b32_e32 v233, v235
	global_store_dwordx4 v[32:33], v[232:235], off offset:256
	v_mov_b32_e32 v230, v16
	v_mov_b32_e32 v231, v17
	v_mov_b32_e32 v228, v8
	v_mov_b32_e32 v229, v9
	s_nop 1
	v_permlane16_swap_b32_e32 v228, v230
	v_permlane16_swap_b32_e32 v229, v231
	global_store_dwordx4 v[12:13], v[228:231], off
	v_mov_b32_e32 v226, v4
	v_mov_b32_e32 v227, v5
	v_mov_b32_e32 v224, v0
	v_mov_b32_e32 v225, v1
	s_nop 1
	v_permlane16_swap_b32_e32 v224, v226
	v_permlane16_swap_b32_e32 v225, v227
	global_store_dwordx4 v[12:13], v[224:227], off offset:256
	s_cbranch_vccnz .LBB0_1941

.LBB0_1932:
	ds_read_b128 v[128:131], v218
	ds_read_b128 v[132:135], v218 offset:1024
	ds_read_b128 v[136:139], v218 offset:2048
	ds_read_b128 v[140:143], v218 offset:3072
	s_add_u32 s59, s26, 0xfffc0080
	s_addc_u32 s60, s27, -1
	s_cmp_eq_u32 s58, 12
	s_cselect_b32 s61, s19, s60
	s_cselect_b32 s60, s56, s59
	s_cselect_b32 s63, s17, s29
	s_cselect_b32 s62, s57, s28
	v_lshl_add_u64 v[176:177], s[26:27], 0, v[196:197]
	s_add_i32 m0, s36, 0xc000
	ds_read_b128 v[144:147], v219
	ds_read_b128 v[148:151], v219 offset:1024
	ds_read_b128 v[152:155], v219 offset:2048
	ds_read_b128 v[156:159], v219 offset:3072
	ds_read_b128 v[160:163], v219 offset:4096
	ds_read_b128 v[164:167], v219 offset:5120
	ds_read_b128 v[168:171], v219 offset:6144
	ds_read_b128 v[172:175], v219 offset:7168
	global_load_lds_dwordx4 v[176:177], off
	v_lshl_add_u64 v[176:177], v[176:177], 0, s[0:1]
	s_add_i32 m0, s36, 0xe000
	s_nop 0
	global_load_lds_dwordx4 v[176:177], off
	s_waitcnt lgkmcnt(8)
	s_barrier
	s_waitcnt lgkmcnt(0)
	s_setprio 1
	s_waitcnt lgkmcnt(0)
	v_mfma_f32_16x16x32_bf16 v[124:127], v[128:131], v[144:147], v[124:127]
	v_mfma_f32_16x16x32_bf16 v[120:123], v[136:139], v[144:147], v[120:123]
	v_mfma_f32_16x16x32_bf16 v[116:119], v[128:131], v[152:155], v[116:119]
	v_mfma_f32_16x16x32_bf16 v[112:115], v[136:139], v[152:155], v[112:115]
	v_mfma_f32_16x16x32_bf16 v[104:107], v[128:131], v[160:163], v[104:107]
	v_mfma_f32_16x16x32_bf16 v[92:95], v[136:139], v[160:163], v[92:95]
	v_mfma_f32_16x16x32_bf16 v[80:83], v[128:131], v[168:171], v[80:83]
	v_mfma_f32_16x16x32_bf16 v[72:75], v[136:139], v[168:171], v[72:75]
	v_mfma_f32_16x16x32_bf16 v[124:127], v[132:135], v[148:151], v[124:127]
	v_mfma_f32_16x16x32_bf16 v[120:123], v[140:143], v[148:151], v[120:123]
	v_mfma_f32_16x16x32_bf16 v[116:119], v[132:135], v[156:159], v[116:119]
	v_mfma_f32_16x16x32_bf16 v[112:115], v[140:143], v[156:159], v[112:115]
	v_mfma_f32_16x16x32_bf16 v[104:107], v[132:135], v[164:167], v[104:107]
	v_mfma_f32_16x16x32_bf16 v[92:95], v[140:143], v[164:167], v[92:95]
	v_mfma_f32_16x16x32_bf16 v[80:83], v[132:135], v[172:175], v[80:83]
	v_mfma_f32_16x16x32_bf16 v[72:75], v[140:143], v[172:175], v[72:75]
	s_setprio 0
	s_barrier
	s_add_i32 s59, s54, s35
	v_lshl_add_u64 v[202:203], s[62:63], 0, v[192:193]
	s_mov_b32 m0, s59
	ds_read_b128 v[176:179], v220
	ds_read_b128 v[180:183], v220 offset:1024
	ds_read_b128 v[184:187], v220 offset:2048
	ds_read_b128 v[188:191], v220 offset:3072
	global_load_lds_dwordx4 v[202:203], off
	v_lshl_add_u64 v[204:205], v[202:203], 0, s[0:1]
	s_add_i32 m0, s59, 0x2000
	s_nop 0
	global_load_lds_dwordx4 v[204:205], off
	s_barrier
	s_waitcnt lgkmcnt(0)
	s_setprio 1
	s_waitcnt lgkmcnt(0)
	v_mfma_f32_16x16x32_bf16 v[108:111], v[176:179], v[144:147], v[108:111]
	v_mfma_f32_16x16x32_bf16 v[100:103], v[184:187], v[144:147], v[100:103]
	v_mfma_f32_16x16x32_bf16 v[96:99], v[176:179], v[152:155], v[96:99]
	v_mfma_f32_16x16x32_bf16 v[88:91], v[184:187], v[152:155], v[88:91]
	v_mfma_f32_16x16x32_bf16 v[84:87], v[176:179], v[160:163], v[84:87]
	v_mfma_f32_16x16x32_bf16 v[76:79], v[184:187], v[160:163], v[76:79]
	v_mfma_f32_16x16x32_bf16 v[68:71], v[176:179], v[168:171], v[68:71]
	v_mfma_f32_16x16x32_bf16 v[64:67], v[184:187], v[168:171], v[64:67]
	v_mfma_f32_16x16x32_bf16 v[108:111], v[180:183], v[148:151], v[108:111]
	v_mfma_f32_16x16x32_bf16 v[100:103], v[188:191], v[148:151], v[100:103]
	v_mfma_f32_16x16x32_bf16 v[96:99], v[180:183], v[156:159], v[96:99]
	v_mfma_f32_16x16x32_bf16 v[88:91], v[188:191], v[156:159], v[88:91]
	v_mfma_f32_16x16x32_bf16 v[84:87], v[180:183], v[164:167], v[84:87]
	v_mfma_f32_16x16x32_bf16 v[76:79], v[188:191], v[164:167], v[76:79]
	v_mfma_f32_16x16x32_bf16 v[68:71], v[180:183], v[172:175], v[68:71]
	v_mfma_f32_16x16x32_bf16 v[64:67], v[188:191], v[172:175], v[64:67]
	s_setprio 0
	s_mov_b32 m0, s36
	v_lshl_add_u64 v[204:205], s[60:61], 0, v[192:193]
	s_barrier
	ds_read_b128 v[144:147], v219 offset:16384
	ds_read_b128 v[148:151], v219 offset:17408
	ds_read_b128 v[152:155], v219 offset:18432
	ds_read_b128 v[156:159], v219 offset:19456
	ds_read_b128 v[160:163], v219 offset:20480
	ds_read_b128 v[164:167], v219 offset:21504
	ds_read_b128 v[168:171], v219 offset:22528
	ds_read_b128 v[172:175], v219 offset:23552
	global_load_lds_dwordx4 v[204:205], off
	v_lshl_add_u64 v[206:207], v[204:205], 0, s[0:1]
	s_mov_b32 m0, s37
	s_nop 0
	global_load_lds_dwordx4 v[206:207], off
	s_barrier
	s_waitcnt lgkmcnt(0)
	s_setprio 1
	s_waitcnt lgkmcnt(0)
	v_mfma_f32_16x16x32_bf16 v[60:63], v[128:131], v[144:147], v[60:63]
	v_mfma_f32_16x16x32_bf16 v[56:59], v[136:139], v[144:147], v[56:59]
	v_mfma_f32_16x16x32_bf16 v[44:47], v[128:131], v[152:155], v[44:47]
	v_mfma_f32_16x16x32_bf16 v[40:43], v[136:139], v[152:155], v[40:43]
	v_mfma_f32_16x16x32_bf16 v[28:31], v[128:131], v[160:163], v[28:31]
	v_mfma_f32_16x16x32_bf16 v[24:27], v[136:139], v[160:163], v[24:27]
	v_mfma_f32_16x16x32_bf16 v[16:19], v[128:131], v[168:171], v[16:19]
	v_mfma_f32_16x16x32_bf16 v[8:11], v[136:139], v[168:171], v[8:11]
	v_mfma_f32_16x16x32_bf16 v[60:63], v[132:135], v[148:151], v[60:63]
	v_mfma_f32_16x16x32_bf16 v[56:59], v[140:143], v[148:151], v[56:59]
	v_mfma_f32_16x16x32_bf16 v[44:47], v[132:135], v[156:159], v[44:47]
	v_mfma_f32_16x16x32_bf16 v[40:43], v[140:143], v[156:159], v[40:43]
	v_mfma_f32_16x16x32_bf16 v[28:31], v[132:135], v[164:167], v[28:31]
	v_mfma_f32_16x16x32_bf16 v[24:27], v[140:143], v[164:167], v[24:27]
	v_mfma_f32_16x16x32_bf16 v[16:19], v[132:135], v[172:175], v[16:19]
	v_mfma_f32_16x16x32_bf16 v[8:11], v[140:143], v[172:175], v[8:11]
	s_setprio 0
	s_barrier
	s_add_i32 s59, s55, s35
	v_lshl_add_u64 v[128:129], v[202:203], 0, s[4:5]
	s_mov_b32 m0, s59
	s_nop 0
	global_load_lds_dwordx4 v[128:129], off
	v_lshl_add_u64 v[128:129], v[202:203], 0, s[6:7]
	s_add_i32 m0, s59, 0x2000
	s_nop 0
	global_load_lds_dwordx4 v[128:129], off
	s_waitcnt vmcnt(6)
	s_barrier
	s_setprio 1
	v_mfma_f32_16x16x32_bf16 v[52:55], v[176:179], v[144:147], v[52:55]
	v_mfma_f32_16x16x32_bf16 v[48:51], v[184:187], v[144:147], v[48:51]
	v_mfma_f32_16x16x32_bf16 v[36:39], v[176:179], v[152:155], v[36:39]
	v_mfma_f32_16x16x32_bf16 v[32:35], v[184:187], v[152:155], v[32:35]
	v_mfma_f32_16x16x32_bf16 v[20:23], v[176:179], v[160:163], v[20:23]
	v_mfma_f32_16x16x32_bf16 v[12:15], v[184:187], v[160:163], v[12:15]
	v_mfma_f32_16x16x32_bf16 v[4:7], v[176:179], v[168:171], v[4:7]
	v_mfma_f32_16x16x32_bf16 v[0:3], v[184:187], v[168:171], v[0:3]
	v_mfma_f32_16x16x32_bf16 v[52:55], v[180:183], v[148:151], v[52:55]
	v_mfma_f32_16x16x32_bf16 v[48:51], v[188:191], v[148:151], v[48:51]
	v_mfma_f32_16x16x32_bf16 v[36:39], v[180:183], v[156:159], v[36:39]
	v_mfma_f32_16x16x32_bf16 v[32:35], v[188:191], v[156:159], v[32:35]
	v_mfma_f32_16x16x32_bf16 v[20:23], v[180:183], v[164:167], v[20:23]
	v_mfma_f32_16x16x32_bf16 v[12:15], v[188:191], v[164:167], v[12:15]
	v_mfma_f32_16x16x32_bf16 v[4:7], v[180:183], v[172:175], v[4:7]
	v_mfma_f32_16x16x32_bf16 v[0:3], v[188:191], v[172:175], v[0:3]
	s_setprio 0
	s_add_i32 s59, 0, 0x18000
	v_add_u32_e32 v140, s59, v217
	s_barrier
	ds_read_b128 v[128:131], v140
	ds_read_b128 v[132:135], v140 offset:1024
	ds_read_b128 v[136:139], v140 offset:2048
	ds_read_b128 v[140:143], v140 offset:3072
	s_mov_b32 m0, s38
	v_lshl_add_u64 v[176:177], v[204:205], 0, s[4:5]
	ds_read_b128 v[144:147], v219 offset:32768
	ds_read_b128 v[148:151], v219 offset:33792
	ds_read_b128 v[152:155], v219 offset:34816
	ds_read_b128 v[156:159], v219 offset:35840
	ds_read_b128 v[160:163], v219 offset:36864
	ds_read_b128 v[164:167], v219 offset:37888
	ds_read_b128 v[168:171], v219 offset:38912
	ds_read_b128 v[172:175], v219 offset:39936
	global_load_lds_dwordx4 v[176:177], off
	v_lshl_add_u64 v[176:177], v[204:205], 0, s[6:7]
	s_mov_b32 m0, s39
	s_nop 0
	global_load_lds_dwordx4 v[176:177], off
	s_waitcnt lgkmcnt(8)
	s_barrier
	s_waitcnt lgkmcnt(0)
	s_setprio 1
	s_waitcnt lgkmcnt(0)
	v_mfma_f32_16x16x32_bf16 v[124:127], v[128:131], v[144:147], v[124:127]
	v_mfma_f32_16x16x32_bf16 v[120:123], v[136:139], v[144:147], v[120:123]
	v_mfma_f32_16x16x32_bf16 v[116:119], v[128:131], v[152:155], v[116:119]
	v_mfma_f32_16x16x32_bf16 v[112:115], v[136:139], v[152:155], v[112:115]
	v_mfma_f32_16x16x32_bf16 v[104:107], v[128:131], v[160:163], v[104:107]
	v_mfma_f32_16x16x32_bf16 v[92:95], v[136:139], v[160:163], v[92:95]
	v_mfma_f32_16x16x32_bf16 v[80:83], v[128:131], v[168:171], v[80:83]
	v_mfma_f32_16x16x32_bf16 v[72:75], v[136:139], v[168:171], v[72:75]
	v_mfma_f32_16x16x32_bf16 v[124:127], v[132:135], v[148:151], v[124:127]
	v_mfma_f32_16x16x32_bf16 v[120:123], v[140:143], v[148:151], v[120:123]
	v_mfma_f32_16x16x32_bf16 v[116:119], v[132:135], v[156:159], v[116:119]
	v_mfma_f32_16x16x32_bf16 v[112:115], v[140:143], v[156:159], v[112:115]
	v_mfma_f32_16x16x32_bf16 v[104:107], v[132:135], v[164:167], v[104:107]
	v_mfma_f32_16x16x32_bf16 v[92:95], v[140:143], v[164:167], v[92:95]
	v_mfma_f32_16x16x32_bf16 v[80:83], v[132:135], v[172:175], v[80:83]
	v_mfma_f32_16x16x32_bf16 v[72:75], v[140:143], v[172:175], v[72:75]
	s_setprio 0
	s_barrier
	s_add_i32 s60, 0, 0x1c000
	s_add_i32 s59, s59, s35
	v_add_u32_e32 v188, s60, v217
	v_lshl_add_u64 v[206:207], v[202:203], 0, s[2:3]
	s_mov_b32 m0, s59
	ds_read_b128 v[176:179], v188
	ds_read_b128 v[180:183], v188 offset:1024
	ds_read_b128 v[184:187], v188 offset:2048
	ds_read_b128 v[188:191], v188 offset:3072
	global_load_lds_dwordx4 v[206:207], off
	v_lshl_add_u64 v[206:207], v[202:203], 0, s[8:9]
	s_add_i32 m0, s59, 0x2000
	s_nop 0
	global_load_lds_dwordx4 v[206:207], off
	s_barrier
	s_waitcnt lgkmcnt(0)
	s_setprio 1
	s_waitcnt lgkmcnt(0)
	v_mfma_f32_16x16x32_bf16 v[108:111], v[176:179], v[144:147], v[108:111]
	v_mfma_f32_16x16x32_bf16 v[100:103], v[184:187], v[144:147], v[100:103]
	v_mfma_f32_16x16x32_bf16 v[96:99], v[176:179], v[152:155], v[96:99]
	v_mfma_f32_16x16x32_bf16 v[88:91], v[184:187], v[152:155], v[88:91]
	v_mfma_f32_16x16x32_bf16 v[84:87], v[176:179], v[160:163], v[84:87]
	v_mfma_f32_16x16x32_bf16 v[76:79], v[184:187], v[160:163], v[76:79]
	v_mfma_f32_16x16x32_bf16 v[68:71], v[176:179], v[168:171], v[68:71]
	v_mfma_f32_16x16x32_bf16 v[64:67], v[184:187], v[168:171], v[64:67]
	v_mfma_f32_16x16x32_bf16 v[108:111], v[180:183], v[148:151], v[108:111]
	v_mfma_f32_16x16x32_bf16 v[100:103], v[188:191], v[148:151], v[100:103]
	v_mfma_f32_16x16x32_bf16 v[96:99], v[180:183], v[156:159], v[96:99]
	v_mfma_f32_16x16x32_bf16 v[88:91], v[188:191], v[156:159], v[88:91]
	v_mfma_f32_16x16x32_bf16 v[84:87], v[180:183], v[164:167], v[84:87]
	v_mfma_f32_16x16x32_bf16 v[76:79], v[188:191], v[164:167], v[76:79]
	v_mfma_f32_16x16x32_bf16 v[68:71], v[180:183], v[172:175], v[68:71]
	v_mfma_f32_16x16x32_bf16 v[64:67], v[188:191], v[172:175], v[64:67]
	s_setprio 0
	s_mov_b32 m0, s52
	v_lshl_add_u64 v[206:207], v[204:205], 0, s[2:3]
	s_barrier
	ds_read_b128 v[144:147], v219 offset:49152
	ds_read_b128 v[148:151], v219 offset:50176
	ds_read_b128 v[152:155], v219 offset:51200
	ds_read_b128 v[156:159], v219 offset:52224
	ds_read_b128 v[160:163], v219 offset:53248
	ds_read_b128 v[164:167], v219 offset:54272
	ds_read_b128 v[168:171], v219 offset:55296
	ds_read_b128 v[172:175], v219 offset:56320
	global_load_lds_dwordx4 v[206:207], off
	v_lshl_add_u64 v[204:205], v[204:205], 0, s[8:9]
	s_mov_b32 m0, s53
	s_nop 0
	global_load_lds_dwordx4 v[204:205], off
	s_barrier
	s_waitcnt lgkmcnt(0)
	s_setprio 1
	s_waitcnt lgkmcnt(0)
	v_mfma_f32_16x16x32_bf16 v[60:63], v[128:131], v[144:147], v[60:63]
	v_mfma_f32_16x16x32_bf16 v[56:59], v[136:139], v[144:147], v[56:59]
	v_mfma_f32_16x16x32_bf16 v[44:47], v[128:131], v[152:155], v[44:47]
	v_mfma_f32_16x16x32_bf16 v[40:43], v[136:139], v[152:155], v[40:43]
	v_mfma_f32_16x16x32_bf16 v[28:31], v[128:131], v[160:163], v[28:31]
	v_mfma_f32_16x16x32_bf16 v[24:27], v[136:139], v[160:163], v[24:27]
	v_mfma_f32_16x16x32_bf16 v[16:19], v[128:131], v[168:171], v[16:19]
	v_mfma_f32_16x16x32_bf16 v[8:11], v[136:139], v[168:171], v[8:11]
	v_mfma_f32_16x16x32_bf16 v[60:63], v[132:135], v[148:151], v[60:63]
	v_mfma_f32_16x16x32_bf16 v[56:59], v[140:143], v[148:151], v[56:59]
	v_mfma_f32_16x16x32_bf16 v[44:47], v[132:135], v[156:159], v[44:47]
	v_mfma_f32_16x16x32_bf16 v[40:43], v[140:143], v[156:159], v[40:43]
	v_mfma_f32_16x16x32_bf16 v[28:31], v[132:135], v[164:167], v[28:31]
	v_mfma_f32_16x16x32_bf16 v[24:27], v[140:143], v[164:167], v[24:27]
	v_mfma_f32_16x16x32_bf16 v[16:19], v[132:135], v[172:175], v[16:19]
	v_mfma_f32_16x16x32_bf16 v[8:11], v[140:143], v[172:175], v[8:11]
	s_setprio 0
	s_barrier
	s_add_i32 s59, s60, s35
	v_lshl_add_u64 v[128:129], v[202:203], 0, s[10:11]
	s_mov_b32 m0, s59
	s_nop 0
	global_load_lds_dwordx4 v[128:129], off
	v_lshl_add_u64 v[128:129], v[202:203], 0, s[12:13]
	s_add_i32 m0, s59, 0x2000
	s_nop 0
	global_load_lds_dwordx4 v[128:129], off
	s_waitcnt vmcnt(6)
	s_barrier
	s_setprio 1
	v_mfma_f32_16x16x32_bf16 v[52:55], v[176:179], v[144:147], v[52:55]
	v_mfma_f32_16x16x32_bf16 v[48:51], v[184:187], v[144:147], v[48:51]
	v_mfma_f32_16x16x32_bf16 v[36:39], v[176:179], v[152:155], v[36:39]
	v_mfma_f32_16x16x32_bf16 v[32:35], v[184:187], v[152:155], v[32:35]
	v_mfma_f32_16x16x32_bf16 v[20:23], v[176:179], v[160:163], v[20:23]
	v_mfma_f32_16x16x32_bf16 v[12:15], v[184:187], v[160:163], v[12:15]
	v_mfma_f32_16x16x32_bf16 v[4:7], v[176:179], v[168:171], v[4:7]
	v_mfma_f32_16x16x32_bf16 v[0:3], v[184:187], v[168:171], v[0:3]
	v_mfma_f32_16x16x32_bf16 v[52:55], v[180:183], v[148:151], v[52:55]
	v_mfma_f32_16x16x32_bf16 v[48:51], v[188:191], v[148:151], v[48:51]
	v_mfma_f32_16x16x32_bf16 v[36:39], v[180:183], v[156:159], v[36:39]
	v_mfma_f32_16x16x32_bf16 v[32:35], v[188:191], v[156:159], v[32:35]
	v_mfma_f32_16x16x32_bf16 v[20:23], v[180:183], v[164:167], v[20:23]
	v_mfma_f32_16x16x32_bf16 v[12:15], v[188:191], v[164:167], v[12:15]
	v_mfma_f32_16x16x32_bf16 v[4:7], v[180:183], v[172:175], v[4:7]
	v_mfma_f32_16x16x32_bf16 v[0:3], v[188:191], v[172:175], v[0:3]
	s_setprio 0
	s_add_i32 s58, s58, 2
	s_add_u32 s26, s26, 0x100
	s_addc_u32 s27, s27, 0
	s_add_u32 s28, s28, 0x100
	s_addc_u32 s29, s29, 0
	s_cmp_gt_u32 s58, 13
	s_barrier
	s_cbranch_scc0 .LBB0_1932
	s_mov_b32 s17, 0
	v_mov_b32_e32 v132, s51
	v_mbcnt_lo_u32_b32 v128, -1, s17
	v_mbcnt_hi_u32_b32 v128, -1, v128
	s_lshl_b32 s17, s24, 8
	s_add_i32 s17, s17, s41
	v_and_or_b32 v206, v128, 15, s17
	s_lshl_b32 s17, s25, 8
	v_ashrrev_i32_e32 v128, 2, v128
	s_or_b32 s17, s17, s46
	v_and_b32_e32 v128, -4, v128
	v_add_u32_e32 v204, s17, v128
	v_add_u32_e32 v128, 0xffff8000, v206
	v_ashrrev_i32_e32 v207, 31, v206
	v_cmp_gt_i32_e32 vcc, s47, v206
	v_mov_b32_e32 v133, s49
	v_mov_b32_e32 v134, s50
	v_cndmask_b32_e32 v129, 0, v207, vcc
	v_cndmask_b32_e32 v128, v128, v206, vcc
	v_mov_b32_e32 v135, s48
	v_ashrrev_i32_e32 v205, 31, v204
	v_cndmask_b32_e32 v131, v132, v133, vcc
	v_cndmask_b32_e32 v130, v134, v135, vcc
	v_lshlrev_b64 v[128:129], 12, v[128:129]
	v_lshl_add_u64 v[128:129], v[130:131], 0, v[128:129]
	v_lshlrev_b64 v[208:209], 2, v[204:205]
	v_lshl_add_u64 v[128:129], v[128:129], 0, v[208:209]
	v_or_b32_e32 v214, 16, v206
	global_load_dwordx4 v[164:167], v[128:129], off nt
	global_load_dwordx4 v[160:163], v[128:129], off offset:64 nt
	global_load_dwordx4 v[156:159], v[128:129], off offset:512 nt
	global_load_dwordx4 v[152:155], v[128:129], off offset:576 nt
	v_ashrrev_i32_e32 v215, 31, v214
	v_add_u32_e32 v128, 0xffff8010, v206
	v_cmp_gt_i32_e32 vcc, s47, v214
	v_or_b32_e32 v212, 32, v206
	v_ashrrev_i32_e32 v213, 31, v212
	v_cndmask_b32_e32 v129, 0, v215, vcc
	v_cndmask_b32_e32 v128, v128, v214, vcc
	v_cndmask_b32_e32 v131, v132, v133, vcc
	v_cndmask_b32_e32 v130, v134, v135, vcc
	v_lshlrev_b64 v[128:129], 12, v[128:129]
	v_lshl_add_u64 v[128:129], v[130:131], 0, v[128:129]
	v_lshl_add_u64 v[128:129], v[128:129], 0, v[208:209]
	global_load_dwordx4 v[184:187], v[128:129], off nt
	global_load_dwordx4 v[176:179], v[128:129], off offset:64 nt
	global_load_dwordx4 v[172:175], v[128:129], off offset:512 nt
	global_load_dwordx4 v[168:171], v[128:129], off offset:576 nt
	v_add_u32_e32 v128, 0xffff8020, v206
	v_cmp_gt_i32_e32 vcc, s47, v212
	v_or_b32_e32 v210, 48, v206
	s_movk_i32 s17, 0x7fff
	v_cndmask_b32_e32 v129, 0, v213, vcc
	v_cndmask_b32_e32 v128, v128, v212, vcc
	v_cndmask_b32_e32 v131, v132, v133, vcc
	v_cndmask_b32_e32 v130, v134, v135, vcc
	v_lshlrev_b64 v[128:129], 12, v[128:129]
	v_lshl_add_u64 v[128:129], v[130:131], 0, v[128:129]
	v_lshl_add_u64 v[128:129], v[128:129], 0, v[208:209]
	global_load_dwordx4 v[188:191], v[128:129], off nt
	global_load_dwordx4 v[180:183], v[128:129], off offset:64 nt
	global_load_dwordx4 v[136:139], v[128:129], off offset:512 nt
	s_nop 0
	global_load_dwordx4 v[128:131], v[128:129], off offset:576 nt
	v_cmp_lt_i32_e32 vcc, s17, v210
	s_and_saveexec_b64 s[24:25], vcc
	s_xor_b64 s[24:25], exec, s[24:25]
	v_add_u32_e32 v194, 0xffff8030, v206
	v_lshlrev_b64 v[132:133], 12, v[194:195]
	v_lshl_add_u64 v[132:133], s[50:51], 0, v[132:133]
	v_mov_b32_e32 v211, v195
	s_andn2_saveexec_b64 s[24:25], s[24:25]
	v_ashrrev_i32_e32 v211, 31, v210
	v_lshlrev_b64 v[132:133], 12, v[210:211]
	v_lshl_add_u64 v[132:133], s[48:49], 0, v[132:133]
	s_or_b64 exec, exec, s[24:25]
	v_lshl_add_u64 v[132:133], v[132:133], 0, v[208:209]
	global_load_dwordx4 v[148:151], v[132:133], off nt
	global_load_dwordx4 v[144:147], v[132:133], off offset:64 nt
	global_load_dwordx4 v[140:143], v[132:133], off offset:512 nt
	s_nop 0
	global_load_dwordx4 v[132:135], v[132:133], off offset:576 nt
	v_lshlrev_b64 v[222:223], 11, v[206:207]
	v_lshlrev_b64 v[212:213], 11, v[212:213]
	v_lshlrev_b64 v[202:203], 1, v[204:205]
	v_mbcnt_lo_u32_b32 v232, -1, 0
	v_mbcnt_hi_u32_b32 v232, -1, v232
	v_and_b32_e32 v232, 16, v232
	v_cmp_ne_u32_e64 s[98:99], 0, v232
	s_nop 1
	v_cndmask_b32_e64 v233, 0, -1, s[98:99]
	v_cndmask_b32_e64 v232, 32, -8, s[98:99]
	v_add_co_u32_e64 v202, s[98:99], v202, v232
	s_nop 1
	v_addc_co_u32_e64 v203, s[98:99], v203, v233, s[98:99]
	v_lshlrev_b64 v[214:215], 11, v[214:215]
	s_waitcnt vmcnt(0)
	v_lshl_add_u64 v[222:223], s[44:45], 0, v[222:223]
	v_lshl_add_u64 v[212:213], s[44:45], 0, v[212:213]
	v_pk_fma_f32 v[126:127], v[166:167], s[14:15], v[126:127] op_sel_hi:[1,0,1]
	v_pk_fma_f32 v[124:125], v[164:165], s[14:15], v[124:125] op_sel_hi:[1,0,1]
	v_pk_fma_f32 v[78:79], v[130:131], s[14:15], v[78:79] op_sel_hi:[1,0,1]
	v_pk_fma_f32 v[76:77], v[128:129], s[14:15], v[76:77] op_sel_hi:[1,0,1]
	v_lshl_add_u64 v[214:215], s[44:45], 0, v[214:215]
	v_lshl_add_u64 v[222:223], v[222:223], 0, v[202:203]
	v_pk_fma_f32 v[122:123], v[162:163], s[14:15], v[122:123] op_sel_hi:[1,0,1]
	v_pk_fma_f32 v[120:121], v[160:161], s[14:15], v[120:121] op_sel_hi:[1,0,1]
	v_pk_fma_f32 v[110:111], v[158:159], s[14:15], v[110:111] op_sel_hi:[1,0,1]
	v_pk_fma_f32 v[108:109], v[156:157], s[14:15], v[108:109] op_sel_hi:[1,0,1]
	v_pk_fma_f32 v[102:103], v[154:155], s[14:15], v[102:103] op_sel_hi:[1,0,1]
	v_pk_fma_f32 v[100:101], v[152:153], s[14:15], v[100:101] op_sel_hi:[1,0,1]
	v_pk_fma_f32 v[118:119], v[186:187], s[14:15], v[118:119] op_sel_hi:[1,0,1]
	v_pk_fma_f32 v[116:117], v[184:185], s[14:15], v[116:117] op_sel_hi:[1,0,1]
	v_pk_fma_f32 v[114:115], v[178:179], s[14:15], v[114:115] op_sel_hi:[1,0,1]
	v_pk_fma_f32 v[112:113], v[176:177], s[14:15], v[112:113] op_sel_hi:[1,0,1]
	v_pk_fma_f32 v[98:99], v[174:175], s[14:15], v[98:99] op_sel_hi:[1,0,1]
	v_pk_fma_f32 v[96:97], v[172:173], s[14:15], v[96:97] op_sel_hi:[1,0,1]
	v_pk_fma_f32 v[90:91], v[170:171], s[14:15], v[90:91] op_sel_hi:[1,0,1]
	v_pk_fma_f32 v[88:89], v[168:169], s[14:15], v[88:89] op_sel_hi:[1,0,1]
	v_lshl_add_u64 v[154:155], v[212:213], 0, v[202:203]
	v_pk_fma_f32 v[106:107], v[190:191], s[14:15], v[106:107] op_sel_hi:[1,0,1]
	v_pk_fma_f32 v[104:105], v[188:189], s[14:15], v[104:105] op_sel_hi:[1,0,1]
	v_pk_fma_f32 v[94:95], v[182:183], s[14:15], v[94:95] op_sel_hi:[1,0,1]
	v_pk_fma_f32 v[92:93], v[180:181], s[14:15], v[92:93] op_sel_hi:[1,0,1]
	v_cvt_pk_bf16_f32 v124, v124, v125
	v_cvt_pk_bf16_f32 v125, v126, v127
	v_cvt_pk_bf16_f32 v76, v76, v77
	v_cvt_pk_bf16_f32 v77, v78, v79
	v_lshl_add_u64 v[152:153], v[214:215], 0, v[202:203]
	v_cvt_pk_bf16_f32 v120, v120, v121
	v_cvt_pk_bf16_f32 v121, v122, v123
	v_cvt_pk_bf16_f32 v108, v108, v109
	v_cvt_pk_bf16_f32 v109, v110, v111
	v_cvt_pk_bf16_f32 v100, v100, v101
	v_cvt_pk_bf16_f32 v101, v102, v103
	v_cvt_pk_bf16_f32 v102, v116, v117
	v_cvt_pk_bf16_f32 v103, v118, v119
	v_cvt_pk_bf16_f32 v110, v112, v113
	v_cvt_pk_bf16_f32 v111, v114, v115
	v_cvt_pk_bf16_f32 v96, v96, v97
	v_cvt_pk_bf16_f32 v97, v98, v99
	v_cvt_pk_bf16_f32 v88, v88, v89
	v_cvt_pk_bf16_f32 v89, v90, v91
	v_cvt_pk_bf16_f32 v90, v104, v105
	v_cvt_pk_bf16_f32 v91, v106, v107
	v_cvt_pk_bf16_f32 v92, v92, v93
	v_cvt_pk_bf16_f32 v93, v94, v95
	v_pk_fma_f32 v[86:87], v[138:139], s[14:15], v[86:87] op_sel_hi:[1,0,1]
	v_pk_fma_f32 v[84:85], v[136:137], s[14:15], v[84:85] op_sel_hi:[1,0,1]
	s_movk_i32 s17, 0x7f80
	v_cvt_pk_bf16_f32 v84, v84, v85
	v_cvt_pk_bf16_f32 v85, v86, v87
	v_cmp_gt_i32_e32 vcc, s17, v206
	s_movk_i32 s17, 0x7f70
	v_add_u32_e32 v130, 0xa0, v206
	v_ashrrev_i32_e32 v131, 31, v130
	v_add_u32_e32 v128, 0xb0, v206
	v_mov_b32_e32 v226, v124
	v_mov_b32_e32 v227, v125
	v_mov_b32_e32 v224, v120
	v_mov_b32_e32 v225, v121
	s_nop 1
	v_permlane16_swap_b32_e32 v224, v226
	v_permlane16_swap_b32_e32 v225, v227
	global_store_dwordx4 v[222:223], v[224:227], off
	v_mov_b32_e32 v230, v108
	v_mov_b32_e32 v231, v109
	v_mov_b32_e32 v228, v100
	v_mov_b32_e32 v229, v101
	s_nop 1
	v_permlane16_swap_b32_e32 v228, v230
	v_permlane16_swap_b32_e32 v229, v231
	global_store_dwordx4 v[222:223], v[228:231], off offset:256
	v_mov_b32_e32 v234, v102
	v_mov_b32_e32 v235, v103
	v_mov_b32_e32 v232, v110
	v_mov_b32_e32 v233, v111
	s_nop 1
	v_permlane16_swap_b32_e32 v232, v234
	v_permlane16_swap_b32_e32 v233, v235
	global_store_dwordx4 v[152:153], v[232:235], off
	v_mov_b32_e32 v226, v96
	v_mov_b32_e32 v227, v97
	v_mov_b32_e32 v224, v88
	v_mov_b32_e32 v225, v89
	s_nop 1
	v_permlane16_swap_b32_e32 v224, v226
	v_permlane16_swap_b32_e32 v225, v227
	global_store_dwordx4 v[152:153], v[224:227], off offset:256
	v_mov_b32_e32 v230, v90
	v_mov_b32_e32 v231, v91
	v_mov_b32_e32 v228, v92
	v_mov_b32_e32 v229, v93
	s_nop 1
	v_permlane16_swap_b32_e32 v228, v230
	v_permlane16_swap_b32_e32 v229, v231
	global_store_dwordx4 v[154:155], v[228:231], off
	v_mov_b32_e32 v232, v76
	v_mov_b32_e32 v233, v77
	v_lshlrev_b64 v[76:77], 11, v[210:211]
	v_lshl_add_u64 v[76:77], s[44:45], 0, v[76:77]
	v_pk_fma_f32 v[66:67], v[134:135], s[14:15], v[66:67] op_sel_hi:[1,0,1]
	v_pk_fma_f32 v[64:65], v[132:133], s[14:15], v[64:65] op_sel_hi:[1,0,1]
	v_lshl_add_u64 v[76:77], v[76:77], 0, v[202:203]
	v_pk_fma_f32 v[70:71], v[142:143], s[14:15], v[70:71] op_sel_hi:[1,0,1]
	v_pk_fma_f32 v[68:69], v[140:141], s[14:15], v[68:69] op_sel_hi:[1,0,1]
	v_cvt_pk_bf16_f32 v64, v64, v65
	v_cvt_pk_bf16_f32 v65, v66, v67
	v_add_u32_e32 v134, 0x80, v206
	v_cvt_pk_bf16_f32 v68, v68, v69
	v_cvt_pk_bf16_f32 v69, v70, v71
	v_mov_b32_e32 v224, v64
	v_mov_b32_e32 v225, v65
	v_ashrrev_i32_e32 v135, 31, v134
	v_add_u32_e32 v64, 0xffff8080, v206
	v_mov_b32_e32 v234, v84
	v_mov_b32_e32 v235, v85
	s_nop 1
	v_permlane16_swap_b32_e32 v232, v234
	v_permlane16_swap_b32_e32 v233, v235
	global_store_dwordx4 v[154:155], v[232:235], off offset:256
	v_mov_b32_e32 v226, v68
	v_mov_b32_e32 v227, v69
	s_nop 1
	v_permlane16_swap_b32_e32 v224, v226
	v_permlane16_swap_b32_e32 v225, v227
	global_store_dwordx4 v[76:77], v[224:227], off offset:256
	v_cndmask_b32_e32 v65, 0, v135, vcc
	v_cndmask_b32_e32 v64, v64, v134, vcc
	v_mov_b32_e32 v68, s51
	v_mov_b32_e32 v69, s49
	v_mov_b32_e32 v70, s50
	v_mov_b32_e32 v71, s48
	v_pk_fma_f32 v[78:79], v[150:151], s[14:15], v[82:83] op_sel_hi:[1,0,1]
	v_pk_fma_f32 v[80:81], v[148:149], s[14:15], v[80:81] op_sel_hi:[1,0,1]
	v_pk_fma_f32 v[74:75], v[146:147], s[14:15], v[74:75] op_sel_hi:[1,0,1]
	v_pk_fma_f32 v[72:73], v[144:145], s[14:15], v[72:73] op_sel_hi:[1,0,1]
	v_cndmask_b32_e32 v67, v68, v69, vcc
	v_cndmask_b32_e32 v66, v70, v71, vcc
	v_lshlrev_b64 v[64:65], 12, v[64:65]
	v_cvt_pk_bf16_f32 v80, v80, v81
	v_cvt_pk_bf16_f32 v81, v78, v79
	v_cvt_pk_bf16_f32 v72, v72, v73
	v_cvt_pk_bf16_f32 v73, v74, v75
	v_lshl_add_u64 v[64:65], v[66:67], 0, v[64:65]
	v_mov_b32_e32 v226, v80
	v_mov_b32_e32 v227, v81
	v_mov_b32_e32 v224, v72
	v_mov_b32_e32 v225, v73
	s_nop 1
	v_permlane16_swap_b32_e32 v224, v226
	v_permlane16_swap_b32_e32 v225, v227
	global_store_dwordx4 v[76:77], v[224:227], off
	v_lshl_add_u64 v[64:65], v[64:65], 0, v[208:209]
	v_add_u32_e32 v132, 0x90, v206
	global_load_dwordx4 v[124:127], v[64:65], off nt
	global_load_dwordx4 v[120:123], v[64:65], off offset:64 nt
	global_load_dwordx4 v[116:119], v[64:65], off offset:512 nt
	global_load_dwordx4 v[112:115], v[64:65], off offset:576 nt
	v_ashrrev_i32_e32 v133, 31, v132
	v_add_u32_e32 v64, 0xffff8090, v206
	v_cmp_gt_i32_e32 vcc, s17, v206
	s_movk_i32 s17, 0x7f60
	s_nop 0
	v_cndmask_b32_e32 v65, 0, v133, vcc
	v_cndmask_b32_e32 v64, v64, v132, vcc
	v_cndmask_b32_e32 v67, v68, v69, vcc
	v_cndmask_b32_e32 v66, v70, v71, vcc
	v_lshlrev_b64 v[64:65], 12, v[64:65]
	v_lshl_add_u64 v[64:65], v[66:67], 0, v[64:65]
	v_lshl_add_u64 v[64:65], v[64:65], 0, v[208:209]
	global_load_dwordx4 v[108:111], v[64:65], off nt
	global_load_dwordx4 v[104:107], v[64:65], off offset:64 nt
	global_load_dwordx4 v[100:103], v[64:65], off offset:512 nt
	global_load_dwordx4 v[96:99], v[64:65], off offset:576 nt
	v_add_u32_e32 v64, 0xffff80a0, v206
	v_cmp_gt_i32_e32 vcc, s17, v206
	s_movk_i32 s17, 0x7f4f
	s_nop 0
	v_cndmask_b32_e32 v65, 0, v131, vcc
	v_cndmask_b32_e32 v64, v64, v130, vcc
	v_cndmask_b32_e32 v67, v68, v69, vcc
	v_cndmask_b32_e32 v66, v70, v71, vcc
	v_lshlrev_b64 v[64:65], 12, v[64:65]
	v_lshl_add_u64 v[64:65], v[66:67], 0, v[64:65]
	v_lshl_add_u64 v[64:65], v[64:65], 0, v[208:209]
	global_load_dwordx4 v[92:95], v[64:65], off nt
	global_load_dwordx4 v[88:91], v[64:65], off offset:64 nt
	global_load_dwordx4 v[84:87], v[64:65], off offset:512 nt
	s_nop 0
	global_load_dwordx4 v[64:67], v[64:65], off offset:576 nt
	v_cmp_lt_i32_e32 vcc, s17, v206
	s_and_saveexec_b64 s[24:25], vcc
	s_xor_b64 s[24:25], exec, s[24:25]
	v_add_u32_e32 v194, 0xffff80b0, v206
	v_lshlrev_b64 v[68:69], 12, v[194:195]
	v_lshl_add_u64 v[68:69], s[50:51], 0, v[68:69]
	v_mov_b32_e32 v129, v195
	s_andn2_saveexec_b64 s[24:25], s[24:25]
	s_cbranch_execz .LBB0_1924
	v_ashrrev_i32_e32 v129, 31, v128
	v_lshlrev_b64 v[68:69], 12, v[128:129]
	v_lshl_add_u64 v[68:69], s[48:49], 0, v[68:69]
	s_branch .LBB0_1924

.LBB0_2188:
	ds_read_b128 v[136:139], v195
	ds_read_b128 v[140:143], v195 offset:1024
	ds_read_b128 v[144:147], v195 offset:2048
	ds_read_b128 v[148:151], v195 offset:3072
	s_add_u32 s43, s26, 0xfff58080
	s_addc_u32 s44, s27, -1
	s_cmp_eq_u32 s42, 38
	s_cselect_b32 s45, s23, s44
	s_cselect_b32 s44, s22, s43
	s_cselect_b32 s59, s25, s29
	s_cselect_b32 s58, s24, s28
	v_lshl_add_u64 v[184:185], s[26:27], 0, v[130:131]
	s_add_i32 m0, s36, 0xc000
	ds_read_b128 v[152:155], v196
	ds_read_b128 v[156:159], v196 offset:1024
	ds_read_b128 v[160:163], v196 offset:2048
	ds_read_b128 v[164:167], v196 offset:3072
	ds_read_b128 v[168:171], v196 offset:4096
	ds_read_b128 v[172:175], v196 offset:5120
	ds_read_b128 v[176:179], v196 offset:6144
	ds_read_b128 v[180:183], v196 offset:7168
	global_load_lds_dwordx4 v[184:185], off
	v_lshl_add_u64 v[184:185], v[184:185], 0, s[6:7]
	s_add_i32 m0, s36, 0xe000
	s_nop 0
	global_load_lds_dwordx4 v[184:185], off
	s_waitcnt lgkmcnt(8)
	s_barrier
	s_waitcnt lgkmcnt(0)
	s_setprio 1
	s_waitcnt lgkmcnt(0)
	v_mfma_f32_16x16x32_bf16 v[124:127], v[136:139], v[152:155], v[124:127]
	v_mfma_f32_16x16x32_bf16 v[120:123], v[144:147], v[152:155], v[120:123]
	v_mfma_f32_16x16x32_bf16 v[112:115], v[136:139], v[160:163], v[112:115]
	v_mfma_f32_16x16x32_bf16 v[104:107], v[144:147], v[160:163], v[104:107]
	v_mfma_f32_16x16x32_bf16 v[96:99], v[136:139], v[168:171], v[96:99]
	v_mfma_f32_16x16x32_bf16 v[88:91], v[144:147], v[168:171], v[88:91]
	v_mfma_f32_16x16x32_bf16 v[80:83], v[136:139], v[176:179], v[80:83]
	v_mfma_f32_16x16x32_bf16 v[72:75], v[144:147], v[176:179], v[72:75]
	v_mfma_f32_16x16x32_bf16 v[124:127], v[140:143], v[156:159], v[124:127]
	v_mfma_f32_16x16x32_bf16 v[120:123], v[148:151], v[156:159], v[120:123]
	v_mfma_f32_16x16x32_bf16 v[112:115], v[140:143], v[164:167], v[112:115]
	v_mfma_f32_16x16x32_bf16 v[104:107], v[148:151], v[164:167], v[104:107]
	v_mfma_f32_16x16x32_bf16 v[96:99], v[140:143], v[172:175], v[96:99]
	v_mfma_f32_16x16x32_bf16 v[88:91], v[148:151], v[172:175], v[88:91]
	v_mfma_f32_16x16x32_bf16 v[80:83], v[140:143], v[180:183], v[80:83]
	v_mfma_f32_16x16x32_bf16 v[72:75], v[148:151], v[180:183], v[72:75]
	s_setprio 0
	s_barrier
	s_add_i32 s43, s51, s35
	v_lshl_add_u64 v[192:193], s[58:59], 0, v[128:129]
	s_mov_b32 m0, s43
	ds_read_b128 v[184:187], v197
	ds_read_b128 v[188:191], v197 offset:1024
	ds_read_b128 v[198:201], v197 offset:2048
	ds_read_b128 v[202:205], v197 offset:3072
	global_load_lds_dwordx4 v[192:193], off
	v_lshl_add_u64 v[206:207], v[192:193], 0, s[6:7]
	s_add_i32 m0, s43, 0x2000
	s_nop 0
	global_load_lds_dwordx4 v[206:207], off
	s_barrier
	s_waitcnt lgkmcnt(0)
	s_setprio 1
	s_waitcnt lgkmcnt(0)
	v_mfma_f32_16x16x32_bf16 v[116:119], v[184:187], v[152:155], v[116:119]
	v_mfma_f32_16x16x32_bf16 v[108:111], v[198:201], v[152:155], v[108:111]
	v_mfma_f32_16x16x32_bf16 v[100:103], v[184:187], v[160:163], v[100:103]
	v_mfma_f32_16x16x32_bf16 v[92:95], v[198:201], v[160:163], v[92:95]
	v_mfma_f32_16x16x32_bf16 v[84:87], v[184:187], v[168:171], v[84:87]
	v_mfma_f32_16x16x32_bf16 v[76:79], v[198:201], v[168:171], v[76:79]
	v_mfma_f32_16x16x32_bf16 v[68:71], v[184:187], v[176:179], v[68:71]
	v_mfma_f32_16x16x32_bf16 v[64:67], v[198:201], v[176:179], v[64:67]
	v_mfma_f32_16x16x32_bf16 v[116:119], v[188:191], v[156:159], v[116:119]
	v_mfma_f32_16x16x32_bf16 v[108:111], v[202:205], v[156:159], v[108:111]
	v_mfma_f32_16x16x32_bf16 v[100:103], v[188:191], v[164:167], v[100:103]
	v_mfma_f32_16x16x32_bf16 v[92:95], v[202:205], v[164:167], v[92:95]
	v_mfma_f32_16x16x32_bf16 v[84:87], v[188:191], v[172:175], v[84:87]
	v_mfma_f32_16x16x32_bf16 v[76:79], v[202:205], v[172:175], v[76:79]
	v_mfma_f32_16x16x32_bf16 v[68:71], v[188:191], v[180:183], v[68:71]
	v_mfma_f32_16x16x32_bf16 v[64:67], v[202:205], v[180:183], v[64:67]
	s_setprio 0
	s_mov_b32 m0, s36
	v_lshl_add_u64 v[206:207], s[44:45], 0, v[128:129]
	s_barrier
	ds_read_b128 v[152:155], v196 offset:16384
	ds_read_b128 v[156:159], v196 offset:17408
	ds_read_b128 v[160:163], v196 offset:18432
	ds_read_b128 v[164:167], v196 offset:19456
	ds_read_b128 v[168:171], v196 offset:20480
	ds_read_b128 v[172:175], v196 offset:21504
	ds_read_b128 v[176:179], v196 offset:22528
	ds_read_b128 v[180:183], v196 offset:23552
	global_load_lds_dwordx4 v[206:207], off
	v_lshl_add_u64 v[208:209], v[206:207], 0, s[6:7]
	s_mov_b32 m0, s37
	s_nop 0
	global_load_lds_dwordx4 v[208:209], off
	s_barrier
	s_waitcnt lgkmcnt(0)
	s_setprio 1
	s_waitcnt lgkmcnt(0)
	v_mfma_f32_16x16x32_bf16 v[60:63], v[136:139], v[152:155], v[60:63]
	v_mfma_f32_16x16x32_bf16 v[56:59], v[144:147], v[152:155], v[56:59]
	v_mfma_f32_16x16x32_bf16 v[48:51], v[136:139], v[160:163], v[48:51]
	v_mfma_f32_16x16x32_bf16 v[40:43], v[144:147], v[160:163], v[40:43]
	v_mfma_f32_16x16x32_bf16 v[32:35], v[136:139], v[168:171], v[32:35]
	v_mfma_f32_16x16x32_bf16 v[24:27], v[144:147], v[168:171], v[24:27]
	v_mfma_f32_16x16x32_bf16 v[16:19], v[136:139], v[176:179], v[16:19]
	v_mfma_f32_16x16x32_bf16 v[8:11], v[144:147], v[176:179], v[8:11]
	v_mfma_f32_16x16x32_bf16 v[60:63], v[140:143], v[156:159], v[60:63]
	v_mfma_f32_16x16x32_bf16 v[56:59], v[148:151], v[156:159], v[56:59]
	v_mfma_f32_16x16x32_bf16 v[48:51], v[140:143], v[164:167], v[48:51]
	v_mfma_f32_16x16x32_bf16 v[40:43], v[148:151], v[164:167], v[40:43]
	v_mfma_f32_16x16x32_bf16 v[32:35], v[140:143], v[172:175], v[32:35]
	v_mfma_f32_16x16x32_bf16 v[24:27], v[148:151], v[172:175], v[24:27]
	v_mfma_f32_16x16x32_bf16 v[16:19], v[140:143], v[180:183], v[16:19]
	v_mfma_f32_16x16x32_bf16 v[8:11], v[148:151], v[180:183], v[8:11]
	s_setprio 0
	s_barrier
	s_add_i32 s43, s52, s35
	v_lshl_add_u64 v[136:137], v[192:193], 0, s[8:9]
	s_mov_b32 m0, s43
	s_nop 0
	global_load_lds_dwordx4 v[136:137], off
	v_lshl_add_u64 v[136:137], v[192:193], 0, s[10:11]
	s_add_i32 m0, s43, 0x2000
	s_nop 0
	global_load_lds_dwordx4 v[136:137], off
	s_waitcnt vmcnt(6)
	s_barrier
	s_setprio 1
	v_mfma_f32_16x16x32_bf16 v[52:55], v[184:187], v[152:155], v[52:55]
	v_mfma_f32_16x16x32_bf16 v[44:47], v[198:201], v[152:155], v[44:47]
	v_mfma_f32_16x16x32_bf16 v[36:39], v[184:187], v[160:163], v[36:39]
	v_mfma_f32_16x16x32_bf16 v[28:31], v[198:201], v[160:163], v[28:31]
	v_mfma_f32_16x16x32_bf16 v[20:23], v[184:187], v[168:171], v[20:23]
	v_mfma_f32_16x16x32_bf16 v[12:15], v[198:201], v[168:171], v[12:15]
	v_mfma_f32_16x16x32_bf16 v[4:7], v[184:187], v[176:179], v[4:7]
	v_mfma_f32_16x16x32_bf16 v[0:3], v[198:201], v[176:179], v[0:3]
	v_mfma_f32_16x16x32_bf16 v[52:55], v[188:191], v[156:159], v[52:55]
	v_mfma_f32_16x16x32_bf16 v[44:47], v[202:205], v[156:159], v[44:47]
	v_mfma_f32_16x16x32_bf16 v[36:39], v[188:191], v[164:167], v[36:39]
	v_mfma_f32_16x16x32_bf16 v[28:31], v[202:205], v[164:167], v[28:31]
	v_mfma_f32_16x16x32_bf16 v[20:23], v[188:191], v[172:175], v[20:23]
	v_mfma_f32_16x16x32_bf16 v[12:15], v[202:205], v[172:175], v[12:15]
	v_mfma_f32_16x16x32_bf16 v[4:7], v[188:191], v[180:183], v[4:7]
	v_mfma_f32_16x16x32_bf16 v[0:3], v[202:205], v[180:183], v[0:3]
	s_setprio 0
	s_add_i32 s43, 0, 0x18000
	v_add_u32_e32 v148, s43, v194
	s_barrier
	ds_read_b128 v[136:139], v148
	ds_read_b128 v[140:143], v148 offset:1024
	ds_read_b128 v[144:147], v148 offset:2048
	ds_read_b128 v[148:151], v148 offset:3072
	s_mov_b32 m0, s38
	v_lshl_add_u64 v[184:185], v[206:207], 0, s[8:9]
	ds_read_b128 v[152:155], v196 offset:32768
	ds_read_b128 v[156:159], v196 offset:33792
	ds_read_b128 v[160:163], v196 offset:34816
	ds_read_b128 v[164:167], v196 offset:35840
	ds_read_b128 v[168:171], v196 offset:36864
	ds_read_b128 v[172:175], v196 offset:37888
	ds_read_b128 v[176:179], v196 offset:38912
	ds_read_b128 v[180:183], v196 offset:39936
	global_load_lds_dwordx4 v[184:185], off
	v_lshl_add_u64 v[184:185], v[206:207], 0, s[10:11]
	s_mov_b32 m0, s39
	s_nop 0
	global_load_lds_dwordx4 v[184:185], off
	s_waitcnt lgkmcnt(8)
	s_barrier
	s_waitcnt lgkmcnt(0)
	s_setprio 1
	s_waitcnt lgkmcnt(0)
	v_mfma_f32_16x16x32_bf16 v[124:127], v[136:139], v[152:155], v[124:127]
	v_mfma_f32_16x16x32_bf16 v[120:123], v[144:147], v[152:155], v[120:123]
	v_mfma_f32_16x16x32_bf16 v[112:115], v[136:139], v[160:163], v[112:115]
	v_mfma_f32_16x16x32_bf16 v[104:107], v[144:147], v[160:163], v[104:107]
	v_mfma_f32_16x16x32_bf16 v[96:99], v[136:139], v[168:171], v[96:99]
	v_mfma_f32_16x16x32_bf16 v[88:91], v[144:147], v[168:171], v[88:91]
	v_mfma_f32_16x16x32_bf16 v[80:83], v[136:139], v[176:179], v[80:83]
	v_mfma_f32_16x16x32_bf16 v[72:75], v[144:147], v[176:179], v[72:75]
	v_mfma_f32_16x16x32_bf16 v[124:127], v[140:143], v[156:159], v[124:127]
	v_mfma_f32_16x16x32_bf16 v[120:123], v[148:151], v[156:159], v[120:123]
	v_mfma_f32_16x16x32_bf16 v[112:115], v[140:143], v[164:167], v[112:115]
	v_mfma_f32_16x16x32_bf16 v[104:107], v[148:151], v[164:167], v[104:107]
	v_mfma_f32_16x16x32_bf16 v[96:99], v[140:143], v[172:175], v[96:99]
	v_mfma_f32_16x16x32_bf16 v[88:91], v[148:151], v[172:175], v[88:91]
	v_mfma_f32_16x16x32_bf16 v[80:83], v[140:143], v[180:183], v[80:83]
	v_mfma_f32_16x16x32_bf16 v[72:75], v[148:151], v[180:183], v[72:75]
	s_setprio 0
	s_barrier
	s_add_i32 s44, 0, 0x1c000
	s_add_i32 s43, s43, s35
	v_add_u32_e32 v202, s44, v194
	v_lshl_add_u64 v[208:209], v[192:193], 0, s[12:13]
	s_mov_b32 m0, s43
	ds_read_b128 v[184:187], v202
	ds_read_b128 v[188:191], v202 offset:1024
	ds_read_b128 v[198:201], v202 offset:2048
	ds_read_b128 v[202:205], v202 offset:3072
	global_load_lds_dwordx4 v[208:209], off
	v_lshl_add_u64 v[208:209], v[192:193], 0, s[14:15]
	s_add_i32 m0, s43, 0x2000
	s_nop 0
	global_load_lds_dwordx4 v[208:209], off
	s_barrier
	s_waitcnt lgkmcnt(0)
	s_setprio 1
	s_waitcnt lgkmcnt(0)
	v_mfma_f32_16x16x32_bf16 v[116:119], v[184:187], v[152:155], v[116:119]
	v_mfma_f32_16x16x32_bf16 v[108:111], v[198:201], v[152:155], v[108:111]
	v_mfma_f32_16x16x32_bf16 v[100:103], v[184:187], v[160:163], v[100:103]
	v_mfma_f32_16x16x32_bf16 v[92:95], v[198:201], v[160:163], v[92:95]
	v_mfma_f32_16x16x32_bf16 v[84:87], v[184:187], v[168:171], v[84:87]
	v_mfma_f32_16x16x32_bf16 v[76:79], v[198:201], v[168:171], v[76:79]
	v_mfma_f32_16x16x32_bf16 v[68:71], v[184:187], v[176:179], v[68:71]
	v_mfma_f32_16x16x32_bf16 v[64:67], v[198:201], v[176:179], v[64:67]
	v_mfma_f32_16x16x32_bf16 v[116:119], v[188:191], v[156:159], v[116:119]
	v_mfma_f32_16x16x32_bf16 v[108:111], v[202:205], v[156:159], v[108:111]
	v_mfma_f32_16x16x32_bf16 v[100:103], v[188:191], v[164:167], v[100:103]
	v_mfma_f32_16x16x32_bf16 v[92:95], v[202:205], v[164:167], v[92:95]
	v_mfma_f32_16x16x32_bf16 v[84:87], v[188:191], v[172:175], v[84:87]
	v_mfma_f32_16x16x32_bf16 v[76:79], v[202:205], v[172:175], v[76:79]
	v_mfma_f32_16x16x32_bf16 v[68:71], v[188:191], v[180:183], v[68:71]
	v_mfma_f32_16x16x32_bf16 v[64:67], v[202:205], v[180:183], v[64:67]
	s_setprio 0
	s_mov_b32 m0, s49
	v_lshl_add_u64 v[208:209], v[206:207], 0, s[12:13]
	s_barrier
	ds_read_b128 v[152:155], v196 offset:49152
	ds_read_b128 v[156:159], v196 offset:50176
	ds_read_b128 v[160:163], v196 offset:51200
	ds_read_b128 v[164:167], v196 offset:52224
	ds_read_b128 v[168:171], v196 offset:53248
	ds_read_b128 v[172:175], v196 offset:54272
	ds_read_b128 v[176:179], v196 offset:55296
	ds_read_b128 v[180:183], v196 offset:56320
	global_load_lds_dwordx4 v[208:209], off
	v_lshl_add_u64 v[206:207], v[206:207], 0, s[14:15]
	s_mov_b32 m0, s50
	s_nop 0
	global_load_lds_dwordx4 v[206:207], off
	s_barrier
	s_waitcnt lgkmcnt(0)
	s_setprio 1
	s_waitcnt lgkmcnt(0)
	v_mfma_f32_16x16x32_bf16 v[60:63], v[136:139], v[152:155], v[60:63]
	v_mfma_f32_16x16x32_bf16 v[56:59], v[144:147], v[152:155], v[56:59]
	v_mfma_f32_16x16x32_bf16 v[48:51], v[136:139], v[160:163], v[48:51]
	v_mfma_f32_16x16x32_bf16 v[40:43], v[144:147], v[160:163], v[40:43]
	v_mfma_f32_16x16x32_bf16 v[32:35], v[136:139], v[168:171], v[32:35]
	v_mfma_f32_16x16x32_bf16 v[24:27], v[144:147], v[168:171], v[24:27]
	v_mfma_f32_16x16x32_bf16 v[16:19], v[136:139], v[176:179], v[16:19]
	v_mfma_f32_16x16x32_bf16 v[8:11], v[144:147], v[176:179], v[8:11]
	v_mfma_f32_16x16x32_bf16 v[60:63], v[140:143], v[156:159], v[60:63]
	v_mfma_f32_16x16x32_bf16 v[56:59], v[148:151], v[156:159], v[56:59]
	v_mfma_f32_16x16x32_bf16 v[48:51], v[140:143], v[164:167], v[48:51]
	v_mfma_f32_16x16x32_bf16 v[40:43], v[148:151], v[164:167], v[40:43]
	v_mfma_f32_16x16x32_bf16 v[32:35], v[140:143], v[172:175], v[32:35]
	v_mfma_f32_16x16x32_bf16 v[24:27], v[148:151], v[172:175], v[24:27]
	v_mfma_f32_16x16x32_bf16 v[16:19], v[140:143], v[180:183], v[16:19]
	v_mfma_f32_16x16x32_bf16 v[8:11], v[148:151], v[180:183], v[8:11]
	s_setprio 0
	s_barrier
	s_add_i32 s43, s44, s35
	v_lshl_add_u64 v[136:137], v[192:193], 0, s[16:17]
	s_mov_b32 m0, s43
	s_nop 0
	global_load_lds_dwordx4 v[136:137], off
	v_lshl_add_u64 v[136:137], v[192:193], 0, s[18:19]
	s_add_i32 m0, s43, 0x2000
	s_nop 0
	global_load_lds_dwordx4 v[136:137], off
	s_waitcnt vmcnt(6)
	s_barrier
	s_setprio 1
	v_mfma_f32_16x16x32_bf16 v[52:55], v[184:187], v[152:155], v[52:55]
	v_mfma_f32_16x16x32_bf16 v[44:47], v[198:201], v[152:155], v[44:47]
	v_mfma_f32_16x16x32_bf16 v[36:39], v[184:187], v[160:163], v[36:39]
	v_mfma_f32_16x16x32_bf16 v[28:31], v[198:201], v[160:163], v[28:31]
	v_mfma_f32_16x16x32_bf16 v[20:23], v[184:187], v[168:171], v[20:23]
	v_mfma_f32_16x16x32_bf16 v[12:15], v[198:201], v[168:171], v[12:15]
	v_mfma_f32_16x16x32_bf16 v[4:7], v[184:187], v[176:179], v[4:7]
	v_mfma_f32_16x16x32_bf16 v[0:3], v[198:201], v[176:179], v[0:3]
	v_mfma_f32_16x16x32_bf16 v[52:55], v[188:191], v[156:159], v[52:55]
	v_mfma_f32_16x16x32_bf16 v[44:47], v[202:205], v[156:159], v[44:47]
	v_mfma_f32_16x16x32_bf16 v[36:39], v[188:191], v[164:167], v[36:39]
	v_mfma_f32_16x16x32_bf16 v[28:31], v[202:205], v[164:167], v[28:31]
	v_mfma_f32_16x16x32_bf16 v[20:23], v[188:191], v[172:175], v[20:23]
	v_mfma_f32_16x16x32_bf16 v[12:15], v[202:205], v[172:175], v[12:15]
	v_mfma_f32_16x16x32_bf16 v[4:7], v[188:191], v[180:183], v[4:7]
	v_mfma_f32_16x16x32_bf16 v[0:3], v[202:205], v[180:183], v[0:3]
	s_setprio 0
	s_add_i32 s42, s42, 2
	s_add_u32 s26, s26, 0x100
	s_addc_u32 s27, s27, 0
	s_add_u32 s28, s28, 0x100
	s_addc_u32 s29, s29, 0
	s_cmp_gt_u32 s42, 39
	s_barrier
	s_cbranch_scc0 .LBB0_2188
	s_mov_b32 s26, 0
	s_and_b64 vcc, exec, s[40:41]
	v_mbcnt_lo_u32_b32 v136, -1, s26
	v_mbcnt_hi_u32_b32 v136, -1, v136
	s_lshl_b32 s26, s55, 8
	s_add_i32 s26, s26, s47
	v_and_or_b32 v138, v136, 15, s26
	s_lshl_b32 s26, s56, 8
	v_ashrrev_i32_e32 v136, 2, v136
	s_or_b32 s26, s26, s48
	v_and_b32_e32 v136, -4, v136
	v_add_u32_e32 v136, s26, v136
	v_ashrrev_i32_e32 v137, 31, v136
	v_lshlrev_b64 v[136:137], 1, v[136:137]
	v_ashrrev_i32_e32 v139, 31, v138
	v_mbcnt_lo_u32_b32 v232, -1, 0
	v_mbcnt_hi_u32_b32 v232, -1, v232
	v_and_b32_e32 v232, 16, v232
	v_cmp_ne_u32_e64 s[98:99], 0, v232
	s_nop 1
	v_cndmask_b32_e64 v233, 0, -1, s[98:99]
	v_cndmask_b32_e64 v232, 32, -8, s[98:99]
	v_add_co_u32_e64 v136, s[98:99], v136, v232
	s_nop 1
	v_addc_co_u32_e64 v137, s[98:99], v137, v233, s[98:99]
	v_lshl_add_u64 v[140:141], s[0:1], 0, v[136:137]
	v_lshlrev_b64 v[198:199], 11, v[138:139]
	v_lshl_add_u64 v[142:143], v[140:141], 0, v[198:199]
	global_load_dwordx4 v[200:203], v[142:143], off
	global_load_dwordx4 v[204:207], v[142:143], off offset:256
	v_or_b32_e32 v142, 16, v138
	v_ashrrev_i32_e32 v143, 31, v142
	v_lshlrev_b64 v[208:209], 11, v[142:143]
	v_lshl_add_u64 v[142:143], v[140:141], 0, v[208:209]
	global_load_dwordx4 v[210:213], v[142:143], off
	global_load_dwordx4 v[214:217], v[142:143], off offset:256
	v_or_b32_e32 v142, 32, v138
	v_or_b32_e32 v138, 48, v138
	v_ashrrev_i32_e32 v143, 31, v142
	v_ashrrev_i32_e32 v139, 31, v138
	v_lshlrev_b64 v[218:219], 11, v[142:143]
	v_lshlrev_b64 v[186:187], 11, v[138:139]
	s_mov_b64 s[26:27], 0x40000
	v_lshl_add_u64 v[142:143], v[140:141], 0, v[218:219]
	v_lshl_add_u64 v[138:139], v[140:141], 0, v[186:187]
	v_lshl_add_u64 v[176:177], v[198:199], 0, s[26:27]
	s_mov_b64 s[26:27], 0x48000
	global_load_dwordx4 v[224:227], v[142:143], off
	global_load_dwordx4 v[188:191], v[142:143], off offset:256
	global_load_dwordx4 v[182:185], v[138:139], off
	global_load_dwordx4 v[178:181], v[138:139], off offset:256
	v_lshl_add_u64 v[138:139], v[140:141], 0, v[176:177]
	v_lshl_add_u64 v[166:167], v[198:199], 0, s[26:27]
	s_mov_b64 s[26:27], 0x50000
	global_load_dwordx4 v[172:175], v[138:139], off
	global_load_dwordx4 v[168:171], v[138:139], off offset:256
	v_lshl_add_u64 v[138:139], v[140:141], 0, v[166:167]
	v_lshl_add_u64 v[156:157], v[198:199], 0, s[26:27]
	s_mov_b64 s[26:27], 0x58000
	global_load_dwordx4 v[162:165], v[138:139], off
	global_load_dwordx4 v[158:161], v[138:139], off offset:256
	v_lshl_add_u64 v[138:139], v[140:141], 0, v[156:157]
	v_lshl_add_u64 v[146:147], v[198:199], 0, s[26:27]
	global_load_dwordx4 v[152:155], v[138:139], off
	global_load_dwordx4 v[148:151], v[138:139], off offset:256
	v_lshl_add_u64 v[138:139], v[140:141], 0, v[146:147]
	global_load_dwordx4 v[142:145], v[138:139], off
	global_load_dwordx4 v[138:141], v[138:139], off offset:256
	s_nop 0
	v_lshl_add_u64 v[198:199], s[4:5], 0, v[198:199]
	v_lshl_add_u64 v[198:199], v[198:199], 0, v[136:137]
	s_mov_b32 s56, s53
	s_mov_b32 s55, s54
	s_mov_b64 s[28:29], s[24:25]
	s_mov_b64 s[26:27], s[22:23]
	s_waitcnt vmcnt(0)
	v_permlane16_swap_b32_e32 v200, v202
	v_permlane16_swap_b32_e32 v201, v203
	v_swap_b32 v200, v202
	v_swap_b32 v201, v203
	v_permlane16_swap_b32_e32 v204, v206
	v_permlane16_swap_b32_e32 v205, v207
	v_swap_b32 v204, v206
	v_swap_b32 v205, v207
	v_permlane16_swap_b32_e32 v210, v212
	v_permlane16_swap_b32_e32 v211, v213
	v_swap_b32 v210, v212
	v_swap_b32 v211, v213
	v_permlane16_swap_b32_e32 v214, v216
	v_permlane16_swap_b32_e32 v215, v217
	v_swap_b32 v214, v216
	v_swap_b32 v215, v217
	v_permlane16_swap_b32_e32 v224, v226
	v_permlane16_swap_b32_e32 v225, v227
	v_mov_b32_e32 v192, v224
	v_mov_b32_e32 v193, v225
	v_mov_b32_e32 v220, v226
	v_mov_b32_e32 v221, v227
	v_permlane16_swap_b32_e32 v188, v190
	v_permlane16_swap_b32_e32 v189, v191
	v_permlane16_swap_b32_e32 v182, v184
	v_permlane16_swap_b32_e32 v183, v185
	v_permlane16_swap_b32_e32 v178, v180
	v_permlane16_swap_b32_e32 v179, v181
	v_permlane16_swap_b32_e32 v172, v174
	v_permlane16_swap_b32_e32 v173, v175
	v_permlane16_swap_b32_e32 v168, v170
	v_permlane16_swap_b32_e32 v169, v171
	v_permlane16_swap_b32_e32 v162, v164
	v_permlane16_swap_b32_e32 v163, v165
	v_permlane16_swap_b32_e32 v158, v160
	v_permlane16_swap_b32_e32 v159, v161
	v_permlane16_swap_b32_e32 v152, v154
	v_permlane16_swap_b32_e32 v153, v155
	v_permlane16_swap_b32_e32 v148, v150
	v_permlane16_swap_b32_e32 v149, v151
	v_permlane16_swap_b32_e32 v142, v144
	v_permlane16_swap_b32_e32 v143, v145
	v_permlane16_swap_b32_e32 v138, v140
	v_permlane16_swap_b32_e32 v139, v141
	s_nop 0
	v_lshlrev_b32_e32 v222, 16, v200
	v_and_b32_e32 v223, 0xffff0000, v200
	v_lshlrev_b32_e32 v200, 16, v201
	v_and_b32_e32 v201, 0xffff0000, v201
	v_pk_fma_f32 v[126:127], v[200:201], s[20:21], v[126:127] op_sel_hi:[1,0,1]
	v_pk_fma_f32 v[124:125], v[222:223], s[20:21], v[124:125] op_sel_hi:[1,0,1]
	s_nop 0
	v_cvt_pk_bf16_f32 v226, v124, v125
	v_cvt_pk_bf16_f32 v227, v126, v127
	v_lshlrev_b32_e32 v124, 16, v202
	v_and_b32_e32 v125, 0xffff0000, v202
	v_lshlrev_b32_e32 v126, 16, v203
	v_and_b32_e32 v127, 0xffff0000, v203
	v_pk_fma_f32 v[122:123], v[126:127], s[20:21], v[122:123] op_sel_hi:[1,0,1]
	v_pk_fma_f32 v[120:121], v[124:125], s[20:21], v[120:121] op_sel_hi:[1,0,1]
	s_nop 0
	v_cvt_pk_bf16_f32 v224, v120, v121
	v_cvt_pk_bf16_f32 v225, v122, v123
	s_nop 1
	v_permlane16_swap_b32_e32 v224, v226
	v_permlane16_swap_b32_e32 v225, v227
	global_store_dwordx4 v[198:199], v[224:227], off
	v_lshlrev_b32_e32 v120, 16, v204
	v_and_b32_e32 v121, 0xffff0000, v204
	v_lshlrev_b32_e32 v122, 16, v205
	v_and_b32_e32 v123, 0xffff0000, v205
	v_pk_fma_f32 v[118:119], v[122:123], s[20:21], v[118:119] op_sel_hi:[1,0,1]
	v_pk_fma_f32 v[116:117], v[120:121], s[20:21], v[116:117] op_sel_hi:[1,0,1]
	s_nop 0
	v_cvt_pk_bf16_f32 v226, v116, v117
	v_cvt_pk_bf16_f32 v227, v118, v119
	v_lshlrev_b32_e32 v116, 16, v206
	v_and_b32_e32 v117, 0xffff0000, v206
	v_lshlrev_b32_e32 v118, 16, v207
	v_and_b32_e32 v119, 0xffff0000, v207
	v_pk_fma_f32 v[110:111], v[118:119], s[20:21], v[110:111] op_sel_hi:[1,0,1]
	v_pk_fma_f32 v[108:109], v[116:117], s[20:21], v[108:109] op_sel_hi:[1,0,1]
	v_lshlrev_b32_e32 v116, 16, v211
	v_cvt_pk_bf16_f32 v224, v108, v109
	v_cvt_pk_bf16_f32 v225, v110, v111
	v_lshlrev_b32_e32 v110, 16, v210
	v_and_b32_e32 v111, 0xffff0000, v210
	v_and_b32_e32 v117, 0xffff0000, v211
	s_nop 1
	v_permlane16_swap_b32_e32 v224, v226
	v_permlane16_swap_b32_e32 v225, v227
	global_store_dwordx4 v[198:199], v[224:227], off offset:256
	v_lshl_add_u64 v[108:109], s[4:5], 0, v[208:209]
	v_pk_fma_f32 v[114:115], v[116:117], s[20:21], v[114:115] op_sel_hi:[1,0,1]
	v_pk_fma_f32 v[110:111], v[110:111], s[20:21], v[112:113] op_sel_hi:[1,0,1]
	v_lshl_add_u64 v[108:109], v[108:109], 0, v[136:137]
	v_cvt_pk_bf16_f32 v226, v110, v111
	v_cvt_pk_bf16_f32 v227, v114, v115
	v_lshlrev_b32_e32 v110, 16, v212
	v_and_b32_e32 v111, 0xffff0000, v212
	v_lshlrev_b32_e32 v112, 16, v213
	v_and_b32_e32 v113, 0xffff0000, v213
	v_pk_fma_f32 v[106:107], v[112:113], s[20:21], v[106:107] op_sel_hi:[1,0,1]
	v_pk_fma_f32 v[104:105], v[110:111], s[20:21], v[104:105] op_sel_hi:[1,0,1]
	s_nop 0
	v_cvt_pk_bf16_f32 v224, v104, v105
	v_cvt_pk_bf16_f32 v225, v106, v107
	s_nop 1
	v_permlane16_swap_b32_e32 v224, v226
	v_permlane16_swap_b32_e32 v225, v227
	global_store_dwordx4 v[108:109], v[224:227], off
	v_lshlrev_b32_e32 v104, 16, v214
	v_and_b32_e32 v105, 0xffff0000, v214
	v_lshlrev_b32_e32 v106, 16, v215
	v_and_b32_e32 v107, 0xffff0000, v215
	v_pk_fma_f32 v[102:103], v[106:107], s[20:21], v[102:103] op_sel_hi:[1,0,1]
	v_pk_fma_f32 v[100:101], v[104:105], s[20:21], v[100:101] op_sel_hi:[1,0,1]
	s_nop 0
	v_cvt_pk_bf16_f32 v226, v100, v101
	v_cvt_pk_bf16_f32 v227, v102, v103
	v_lshlrev_b32_e32 v100, 16, v216
	v_and_b32_e32 v101, 0xffff0000, v216
	v_lshlrev_b32_e32 v102, 16, v217
	v_and_b32_e32 v103, 0xffff0000, v217
	v_pk_fma_f32 v[94:95], v[102:103], s[20:21], v[94:95] op_sel_hi:[1,0,1]
	v_pk_fma_f32 v[92:93], v[100:101], s[20:21], v[92:93] op_sel_hi:[1,0,1]
	v_lshlrev_b32_e32 v100, 16, v221
	v_cvt_pk_bf16_f32 v224, v92, v93
	v_cvt_pk_bf16_f32 v225, v94, v95
	v_lshlrev_b32_e32 v94, 16, v220
	v_and_b32_e32 v95, 0xffff0000, v220
	v_and_b32_e32 v101, 0xffff0000, v221
	s_nop 1
	v_permlane16_swap_b32_e32 v224, v226
	v_permlane16_swap_b32_e32 v225, v227
	global_store_dwordx4 v[108:109], v[224:227], off offset:256
	v_lshl_add_u64 v[92:93], s[4:5], 0, v[218:219]
	v_pk_fma_f32 v[98:99], v[100:101], s[20:21], v[98:99] op_sel_hi:[1,0,1]
	v_pk_fma_f32 v[94:95], v[94:95], s[20:21], v[96:97] op_sel_hi:[1,0,1]
	v_lshl_add_u64 v[92:93], v[92:93], 0, v[136:137]
	v_cvt_pk_bf16_f32 v226, v94, v95
	v_cvt_pk_bf16_f32 v227, v98, v99
	v_lshlrev_b32_e32 v94, 16, v192
	v_and_b32_e32 v95, 0xffff0000, v192
	v_lshlrev_b32_e32 v96, 16, v193
	v_and_b32_e32 v97, 0xffff0000, v193
	v_pk_fma_f32 v[90:91], v[96:97], s[20:21], v[90:91] op_sel_hi:[1,0,1]
	v_pk_fma_f32 v[88:89], v[94:95], s[20:21], v[88:89] op_sel_hi:[1,0,1]
	s_nop 0
	v_cvt_pk_bf16_f32 v224, v88, v89
	v_cvt_pk_bf16_f32 v225, v90, v91
	s_nop 1
	v_permlane16_swap_b32_e32 v224, v226
	v_permlane16_swap_b32_e32 v225, v227
	global_store_dwordx4 v[92:93], v[224:227], off
	v_lshlrev_b32_e32 v88, 16, v190
	v_and_b32_e32 v89, 0xffff0000, v190
	v_lshlrev_b32_e32 v90, 16, v191
	v_and_b32_e32 v91, 0xffff0000, v191
	v_pk_fma_f32 v[86:87], v[90:91], s[20:21], v[86:87] op_sel_hi:[1,0,1]
	v_pk_fma_f32 v[84:85], v[88:89], s[20:21], v[84:85] op_sel_hi:[1,0,1]
	s_nop 0
	v_cvt_pk_bf16_f32 v226, v84, v85
	v_cvt_pk_bf16_f32 v227, v86, v87
	v_lshlrev_b32_e32 v84, 16, v188
	v_and_b32_e32 v85, 0xffff0000, v188
	v_lshlrev_b32_e32 v86, 16, v189
	v_and_b32_e32 v87, 0xffff0000, v189
	v_pk_fma_f32 v[78:79], v[86:87], s[20:21], v[78:79] op_sel_hi:[1,0,1]
	v_pk_fma_f32 v[76:77], v[84:85], s[20:21], v[76:77] op_sel_hi:[1,0,1]
	v_lshlrev_b32_e32 v84, 16, v185
	v_cvt_pk_bf16_f32 v224, v76, v77
	v_cvt_pk_bf16_f32 v225, v78, v79
	v_lshlrev_b32_e32 v78, 16, v184
	v_and_b32_e32 v79, 0xffff0000, v184
	v_and_b32_e32 v85, 0xffff0000, v185
	s_nop 1
	v_permlane16_swap_b32_e32 v224, v226
	v_permlane16_swap_b32_e32 v225, v227
	global_store_dwordx4 v[92:93], v[224:227], off offset:256
	v_lshl_add_u64 v[76:77], s[4:5], 0, v[186:187]
	v_pk_fma_f32 v[82:83], v[84:85], s[20:21], v[82:83] op_sel_hi:[1,0,1]
	v_pk_fma_f32 v[78:79], v[78:79], s[20:21], v[80:81] op_sel_hi:[1,0,1]
	v_lshl_add_u64 v[76:77], v[76:77], 0, v[136:137]
	v_cvt_pk_bf16_f32 v226, v78, v79
	v_cvt_pk_bf16_f32 v227, v82, v83
	v_lshlrev_b32_e32 v78, 16, v182
	v_and_b32_e32 v79, 0xffff0000, v182
	v_lshlrev_b32_e32 v80, 16, v183
	v_and_b32_e32 v81, 0xffff0000, v183
	v_pk_fma_f32 v[74:75], v[80:81], s[20:21], v[74:75] op_sel_hi:[1,0,1]
	v_pk_fma_f32 v[72:73], v[78:79], s[20:21], v[72:73] op_sel_hi:[1,0,1]
	s_nop 0
	v_cvt_pk_bf16_f32 v224, v72, v73
	v_cvt_pk_bf16_f32 v225, v74, v75
	s_nop 1
	v_permlane16_swap_b32_e32 v224, v226
	v_permlane16_swap_b32_e32 v225, v227
	global_store_dwordx4 v[76:77], v[224:227], off
	v_lshlrev_b32_e32 v72, 16, v180
	v_and_b32_e32 v73, 0xffff0000, v180
	v_lshlrev_b32_e32 v74, 16, v181
	v_and_b32_e32 v75, 0xffff0000, v181
	v_pk_fma_f32 v[70:71], v[74:75], s[20:21], v[70:71] op_sel_hi:[1,0,1]
	v_pk_fma_f32 v[68:69], v[72:73], s[20:21], v[68:69] op_sel_hi:[1,0,1]
	s_nop 0
	v_cvt_pk_bf16_f32 v226, v68, v69
	v_cvt_pk_bf16_f32 v227, v70, v71
	v_lshlrev_b32_e32 v68, 16, v178
	v_and_b32_e32 v69, 0xffff0000, v178
	v_lshlrev_b32_e32 v70, 16, v179
	v_and_b32_e32 v71, 0xffff0000, v179
	v_pk_fma_f32 v[66:67], v[70:71], s[20:21], v[66:67] op_sel_hi:[1,0,1]
	v_pk_fma_f32 v[64:65], v[68:69], s[20:21], v[64:65] op_sel_hi:[1,0,1]
	v_lshlrev_b32_e32 v68, 16, v175
	v_cvt_pk_bf16_f32 v224, v64, v65
	v_cvt_pk_bf16_f32 v225, v66, v67
	v_lshlrev_b32_e32 v66, 16, v174
	v_and_b32_e32 v67, 0xffff0000, v174
	v_and_b32_e32 v69, 0xffff0000, v175
	s_nop 1
	v_permlane16_swap_b32_e32 v224, v226
	v_permlane16_swap_b32_e32 v225, v227
	global_store_dwordx4 v[76:77], v[224:227], off offset:256
	v_lshl_add_u64 v[64:65], s[4:5], 0, v[176:177]
	v_pk_fma_f32 v[62:63], v[68:69], s[20:21], v[62:63] op_sel_hi:[1,0,1]
	v_pk_fma_f32 v[60:61], v[66:67], s[20:21], v[60:61] op_sel_hi:[1,0,1]
	v_lshl_add_u64 v[64:65], v[64:65], 0, v[136:137]
	v_cvt_pk_bf16_f32 v226, v60, v61
	v_cvt_pk_bf16_f32 v227, v62, v63
	v_lshlrev_b32_e32 v60, 16, v172
	v_and_b32_e32 v61, 0xffff0000, v172
	v_lshlrev_b32_e32 v62, 16, v173
	v_and_b32_e32 v63, 0xffff0000, v173
	v_pk_fma_f32 v[58:59], v[62:63], s[20:21], v[58:59] op_sel_hi:[1,0,1]
	v_pk_fma_f32 v[56:57], v[60:61], s[20:21], v[56:57] op_sel_hi:[1,0,1]
	s_nop 0
	v_cvt_pk_bf16_f32 v224, v56, v57
	v_cvt_pk_bf16_f32 v225, v58, v59
	s_nop 1
	v_permlane16_swap_b32_e32 v224, v226
	v_permlane16_swap_b32_e32 v225, v227
	global_store_dwordx4 v[64:65], v[224:227], off
	v_lshlrev_b32_e32 v56, 16, v170
	v_and_b32_e32 v57, 0xffff0000, v170
	v_lshlrev_b32_e32 v58, 16, v171
	v_and_b32_e32 v59, 0xffff0000, v171
	v_pk_fma_f32 v[54:55], v[58:59], s[20:21], v[54:55] op_sel_hi:[1,0,1]
	v_pk_fma_f32 v[52:53], v[56:57], s[20:21], v[52:53] op_sel_hi:[1,0,1]
	s_nop 0
	v_cvt_pk_bf16_f32 v226, v52, v53
	v_cvt_pk_bf16_f32 v227, v54, v55
	v_lshlrev_b32_e32 v52, 16, v168
	v_and_b32_e32 v53, 0xffff0000, v168
	v_lshlrev_b32_e32 v54, 16, v169
	v_and_b32_e32 v55, 0xffff0000, v169
	v_pk_fma_f32 v[46:47], v[54:55], s[20:21], v[46:47] op_sel_hi:[1,0,1]
	v_pk_fma_f32 v[44:45], v[52:53], s[20:21], v[44:45] op_sel_hi:[1,0,1]
	v_lshlrev_b32_e32 v52, 16, v165
	v_cvt_pk_bf16_f32 v224, v44, v45
	v_cvt_pk_bf16_f32 v225, v46, v47
	v_lshlrev_b32_e32 v46, 16, v164
	v_and_b32_e32 v47, 0xffff0000, v164
	v_and_b32_e32 v53, 0xffff0000, v165
	s_nop 1
	v_permlane16_swap_b32_e32 v224, v226
	v_permlane16_swap_b32_e32 v225, v227
	global_store_dwordx4 v[64:65], v[224:227], off offset:256
	v_lshl_add_u64 v[44:45], s[4:5], 0, v[166:167]
	v_pk_fma_f32 v[50:51], v[52:53], s[20:21], v[50:51] op_sel_hi:[1,0,1]
	v_pk_fma_f32 v[46:47], v[46:47], s[20:21], v[48:49] op_sel_hi:[1,0,1]
	v_lshl_add_u64 v[44:45], v[44:45], 0, v[136:137]
	v_cvt_pk_bf16_f32 v226, v46, v47
	v_cvt_pk_bf16_f32 v227, v50, v51
	v_lshlrev_b32_e32 v46, 16, v162
	v_and_b32_e32 v47, 0xffff0000, v162
	v_lshlrev_b32_e32 v48, 16, v163
	v_and_b32_e32 v49, 0xffff0000, v163
	v_pk_fma_f32 v[42:43], v[48:49], s[20:21], v[42:43] op_sel_hi:[1,0,1]
	v_pk_fma_f32 v[40:41], v[46:47], s[20:21], v[40:41] op_sel_hi:[1,0,1]
	s_nop 0
	v_cvt_pk_bf16_f32 v224, v40, v41
	v_cvt_pk_bf16_f32 v225, v42, v43
	s_nop 1
	v_permlane16_swap_b32_e32 v224, v226
	v_permlane16_swap_b32_e32 v225, v227
	global_store_dwordx4 v[44:45], v[224:227], off
	v_lshlrev_b32_e32 v40, 16, v160
	v_and_b32_e32 v41, 0xffff0000, v160
	v_lshlrev_b32_e32 v42, 16, v161
	v_and_b32_e32 v43, 0xffff0000, v161
	v_pk_fma_f32 v[38:39], v[42:43], s[20:21], v[38:39] op_sel_hi:[1,0,1]
	v_pk_fma_f32 v[36:37], v[40:41], s[20:21], v[36:37] op_sel_hi:[1,0,1]
	s_nop 0
	v_cvt_pk_bf16_f32 v226, v36, v37
	v_cvt_pk_bf16_f32 v227, v38, v39
	v_lshlrev_b32_e32 v36, 16, v158
	v_and_b32_e32 v37, 0xffff0000, v158
	v_lshlrev_b32_e32 v38, 16, v159
	v_and_b32_e32 v39, 0xffff0000, v159
	v_pk_fma_f32 v[30:31], v[38:39], s[20:21], v[30:31] op_sel_hi:[1,0,1]
	v_pk_fma_f32 v[28:29], v[36:37], s[20:21], v[28:29] op_sel_hi:[1,0,1]
	v_lshlrev_b32_e32 v36, 16, v155
	v_cvt_pk_bf16_f32 v224, v28, v29
	v_cvt_pk_bf16_f32 v225, v30, v31
	v_lshlrev_b32_e32 v30, 16, v154
	v_and_b32_e32 v31, 0xffff0000, v154
	v_and_b32_e32 v37, 0xffff0000, v155
	s_nop 1
	v_permlane16_swap_b32_e32 v224, v226
	v_permlane16_swap_b32_e32 v225, v227
	global_store_dwordx4 v[44:45], v[224:227], off offset:256
	v_lshl_add_u64 v[28:29], s[4:5], 0, v[156:157]
	v_pk_fma_f32 v[34:35], v[36:37], s[20:21], v[34:35] op_sel_hi:[1,0,1]
	v_pk_fma_f32 v[30:31], v[30:31], s[20:21], v[32:33] op_sel_hi:[1,0,1]
	v_lshl_add_u64 v[28:29], v[28:29], 0, v[136:137]
	v_cvt_pk_bf16_f32 v226, v30, v31
	v_cvt_pk_bf16_f32 v227, v34, v35
	v_lshlrev_b32_e32 v30, 16, v152
	v_and_b32_e32 v31, 0xffff0000, v152
	v_lshlrev_b32_e32 v32, 16, v153
	v_and_b32_e32 v33, 0xffff0000, v153
	v_pk_fma_f32 v[26:27], v[32:33], s[20:21], v[26:27] op_sel_hi:[1,0,1]
	v_pk_fma_f32 v[24:25], v[30:31], s[20:21], v[24:25] op_sel_hi:[1,0,1]
	s_nop 0
	v_cvt_pk_bf16_f32 v224, v24, v25
	v_cvt_pk_bf16_f32 v225, v26, v27
	s_nop 1
	v_permlane16_swap_b32_e32 v224, v226
	v_permlane16_swap_b32_e32 v225, v227
	global_store_dwordx4 v[28:29], v[224:227], off
	v_lshlrev_b32_e32 v24, 16, v150
	v_and_b32_e32 v25, 0xffff0000, v150
	v_lshlrev_b32_e32 v26, 16, v151
	v_and_b32_e32 v27, 0xffff0000, v151
	v_pk_fma_f32 v[22:23], v[26:27], s[20:21], v[22:23] op_sel_hi:[1,0,1]
	v_pk_fma_f32 v[20:21], v[24:25], s[20:21], v[20:21] op_sel_hi:[1,0,1]
	s_nop 0
	v_cvt_pk_bf16_f32 v226, v20, v21
	v_cvt_pk_bf16_f32 v227, v22, v23
	v_lshlrev_b32_e32 v20, 16, v148
	v_and_b32_e32 v21, 0xffff0000, v148
	v_lshlrev_b32_e32 v22, 16, v149
	v_and_b32_e32 v23, 0xffff0000, v149
	v_pk_fma_f32 v[14:15], v[22:23], s[20:21], v[14:15] op_sel_hi:[1,0,1]
	v_pk_fma_f32 v[12:13], v[20:21], s[20:21], v[12:13] op_sel_hi:[1,0,1]
	v_lshlrev_b32_e32 v20, 16, v145
	v_cvt_pk_bf16_f32 v224, v12, v13
	v_cvt_pk_bf16_f32 v225, v14, v15
	v_lshlrev_b32_e32 v14, 16, v144
	v_and_b32_e32 v15, 0xffff0000, v144
	v_and_b32_e32 v21, 0xffff0000, v145
	s_nop 1
	v_permlane16_swap_b32_e32 v224, v226
	v_permlane16_swap_b32_e32 v225, v227
	global_store_dwordx4 v[28:29], v[224:227], off offset:256
	v_lshl_add_u64 v[12:13], s[4:5], 0, v[146:147]
	v_pk_fma_f32 v[18:19], v[20:21], s[20:21], v[18:19] op_sel_hi:[1,0,1]
	v_pk_fma_f32 v[14:15], v[14:15], s[20:21], v[16:17] op_sel_hi:[1,0,1]
	v_lshl_add_u64 v[12:13], v[12:13], 0, v[136:137]
	v_cvt_pk_bf16_f32 v226, v14, v15
	v_cvt_pk_bf16_f32 v227, v18, v19
	v_lshlrev_b32_e32 v14, 16, v142
	v_and_b32_e32 v15, 0xffff0000, v142
	v_lshlrev_b32_e32 v16, 16, v143
	v_and_b32_e32 v17, 0xffff0000, v143
	v_pk_fma_f32 v[10:11], v[16:17], s[20:21], v[10:11] op_sel_hi:[1,0,1]
	v_pk_fma_f32 v[8:9], v[14:15], s[20:21], v[8:9] op_sel_hi:[1,0,1]
	s_nop 0
	v_cvt_pk_bf16_f32 v224, v8, v9
	v_cvt_pk_bf16_f32 v225, v10, v11
	s_nop 1
	v_permlane16_swap_b32_e32 v224, v226
	v_permlane16_swap_b32_e32 v225, v227
	global_store_dwordx4 v[12:13], v[224:227], off
	v_lshlrev_b32_e32 v8, 16, v140
	v_and_b32_e32 v9, 0xffff0000, v140
	v_lshlrev_b32_e32 v10, 16, v141
	v_and_b32_e32 v11, 0xffff0000, v141
	v_pk_fma_f32 v[6:7], v[10:11], s[20:21], v[6:7] op_sel_hi:[1,0,1]
	v_pk_fma_f32 v[4:5], v[8:9], s[20:21], v[4:5] op_sel_hi:[1,0,1]
	s_nop 0
	v_cvt_pk_bf16_f32 v226, v4, v5
	v_cvt_pk_bf16_f32 v227, v6, v7
	v_lshlrev_b32_e32 v4, 16, v138
	v_and_b32_e32 v5, 0xffff0000, v138
	v_lshlrev_b32_e32 v6, 16, v139
	v_and_b32_e32 v7, 0xffff0000, v139
	v_pk_fma_f32 v[2:3], v[6:7], s[20:21], v[2:3] op_sel_hi:[1,0,1]
	v_pk_fma_f32 v[0:1], v[4:5], s[20:21], v[0:1] op_sel_hi:[1,0,1]
	s_nop 0
	v_cvt_pk_bf16_f32 v224, v0, v1
	v_cvt_pk_bf16_f32 v225, v2, v3
	s_nop 1
	v_permlane16_swap_b32_e32 v224, v226
	v_permlane16_swap_b32_e32 v225, v227
	global_store_dwordx4 v[12:13], v[224:227], off offset:256
	s_cbranch_vccz .LBB0_2177
	s_waitcnt vmcnt(0)
	s_cmpk_gt_u32 s31, 0xff
	s_cbranch_scc1 .LBB0_2192
	s_barrier
